# GEMM K-loops: first loop trip peeled with SrcC=0 on each accumulator's first MFMA; the per-unit 128-instruction accumulator zeroing removed (on top of map prefetch + chain-tail MFMA hoist)
# speedup vs baseline: 1.0069x; 1.0037x over previous
.LBB0_174:
	s_ashr_i32 s15, s14, 31
	s_lshl_b64 s[16:17], s[14:15], 19
	s_add_u32 s16, s82, s16
	s_addc_u32 s17, s83, s17
	s_and_b64 s[18:19], s[0:1], exec
	s_cselect_b32 s15, s17, s23
	s_cselect_b32 s86, s16, s22
	s_ashr_i32 s13, s12, 31
	s_lshl_b64 s[18:19], s[12:13], 19
	s_add_u32 s18, s33, s18
	s_addc_u32 s19, s38, s19
	s_and_b64 s[26:27], s[0:1], exec
	s_cselect_b32 s13, s19, s25
	s_cselect_b32 s87, s18, s24
	s_add_u32 s22, s22, 0x40080
	s_addc_u32 s23, s23, 0
	s_add_u32 s88, s24, 0x100
	s_addc_u32 s89, s25, 0
	s_mov_b32 s90, -2
	s_nop 0
	s_nop 0
	s_nop 0
	s_nop 0
	s_nop 0
	s_nop 0
	s_nop 0
	s_nop 0
	s_nop 0
	s_nop 0
	s_nop 0
	s_nop 0
	s_nop 0
	s_nop 0
	s_nop 0
	ds_read_b128 v[144:147], v151
	ds_read_b128 v[156:159], v151 offset:1024
	ds_read_b128 v[160:163], v151 offset:2048
	ds_read_b128 v[164:167], v151 offset:3072
	ds_read_b128 v[168:171], v152
	ds_read_b128 v[172:175], v152 offset:1024
	ds_read_b128 v[176:179], v152 offset:2048
	ds_read_b128 v[180:183], v152 offset:3072
	s_add_u32 s24, s22, 0xfffc0080
	s_addc_u32 s25, s23, -1
	s_cmp_eq_u32 s90, 12
	s_cselect_b32 s27, s15, s25
	s_cselect_b32 s26, s86, s24
	s_cselect_b32 s25, s13, s89
	s_cselect_b32 s24, s87, s88
	v_lshl_add_u64 v[204:205], s[22:23], 0, v[136:137]
	s_add_i32 m0, s21, 0xc000
	ds_read_b128 v[184:187], v153
	ds_read_b128 v[188:191], v153 offset:1024
	ds_read_b128 v[192:195], v153 offset:2048
	ds_read_b128 v[196:199], v153 offset:3072
	ds_read_b128 v[200:203], v153 offset:4096
	ds_read_b128 v[208:211], v153 offset:5120
	ds_read_b128 v[212:215], v153 offset:6144
	ds_read_b128 v[216:219], v153 offset:7168
	global_load_lds_dwordx4 v[204:205], off
	v_lshl_add_u64 v[204:205], s[22:23], 0, v[138:139]
	s_add_i32 m0, s21, 0xe000
	s_nop 0
	global_load_lds_dwordx4 v[204:205], off
	s_waitcnt vmcnt(8)
	s_waitcnt lgkmcnt(0)
	s_setprio 1
	s_barrier
	v_mfma_f32_16x16x32_bf16 v[124:127], v[144:147], v[184:187], 0
	v_mfma_f32_16x16x32_bf16 v[120:123], v[160:163], v[184:187], 0
	v_mfma_f32_16x16x32_bf16 v[116:119], v[144:147], v[192:195], 0
	v_mfma_f32_16x16x32_bf16 v[112:115], v[160:163], v[192:195], 0
	v_mfma_f32_16x16x32_bf16 v[104:107], v[144:147], v[200:203], 0
	v_mfma_f32_16x16x32_bf16 v[96:99], v[160:163], v[200:203], 0
	v_mfma_f32_16x16x32_bf16 v[76:79], v[144:147], v[212:215], 0
	v_mfma_f32_16x16x32_bf16 v[72:75], v[160:163], v[212:215], 0
	v_mfma_f32_16x16x32_bf16 v[124:127], v[156:159], v[188:191], v[124:127]
	v_mfma_f32_16x16x32_bf16 v[120:123], v[164:167], v[188:191], v[120:123]
	v_mfma_f32_16x16x32_bf16 v[116:119], v[156:159], v[196:199], v[116:119]
	v_mfma_f32_16x16x32_bf16 v[112:115], v[164:167], v[196:199], v[112:115]
	v_mfma_f32_16x16x32_bf16 v[104:107], v[156:159], v[208:211], v[104:107]
	v_mfma_f32_16x16x32_bf16 v[96:99], v[164:167], v[208:211], v[96:99]
	v_mfma_f32_16x16x32_bf16 v[76:79], v[156:159], v[216:219], v[76:79]
	v_mfma_f32_16x16x32_bf16 v[72:75], v[164:167], v[216:219], v[72:75]
	s_setprio 0
	s_setprio 1
	v_mfma_f32_16x16x32_bf16 v[108:111], v[168:171], v[184:187], 0
	v_mfma_f32_16x16x32_bf16 v[100:103], v[176:179], v[184:187], 0
	v_mfma_f32_16x16x32_bf16 v[92:95], v[168:171], v[192:195], 0
	v_mfma_f32_16x16x32_bf16 v[88:91], v[176:179], v[192:195], 0
	v_mfma_f32_16x16x32_bf16 v[84:87], v[168:171], v[200:203], 0
	v_mfma_f32_16x16x32_bf16 v[80:83], v[176:179], v[200:203], 0
	v_mfma_f32_16x16x32_bf16 v[68:71], v[168:171], v[212:215], 0
	v_mfma_f32_16x16x32_bf16 v[64:67], v[176:179], v[212:215], 0
	v_mfma_f32_16x16x32_bf16 v[108:111], v[172:175], v[188:191], v[108:111]
	v_mfma_f32_16x16x32_bf16 v[100:103], v[180:183], v[188:191], v[100:103]
	v_mfma_f32_16x16x32_bf16 v[92:95], v[172:175], v[196:199], v[92:95]
	v_mfma_f32_16x16x32_bf16 v[88:91], v[180:183], v[196:199], v[88:91]
	v_mfma_f32_16x16x32_bf16 v[84:87], v[172:175], v[208:211], v[84:87]
	v_mfma_f32_16x16x32_bf16 v[80:83], v[180:183], v[208:211], v[80:83]
	v_mfma_f32_16x16x32_bf16 v[68:71], v[172:175], v[216:219], v[68:71]
	v_mfma_f32_16x16x32_bf16 v[64:67], v[180:183], v[216:219], v[64:67]
	s_barrier
	s_setprio 0
	s_add_i32 s91, s79, s30
	v_lshl_add_u64 v[204:205], s[24:25], 0, v[132:133]
	s_mov_b32 m0, s91
	ds_read_b128 v[184:187], v153 offset:16384
	ds_read_b128 v[188:191], v153 offset:17408
	ds_read_b128 v[192:195], v153 offset:18432
	ds_read_b128 v[196:199], v153 offset:19456
	ds_read_b128 v[200:203], v153 offset:20480
	ds_read_b128 v[208:211], v153 offset:21504
	ds_read_b128 v[212:215], v153 offset:22528
	ds_read_b128 v[216:219], v153 offset:23552
	global_load_lds_dwordx4 v[204:205], off
	s_add_i32 m0, s91, 0x2000
	s_add_u32 s92, s24, 0x40000
	v_lshl_add_u64 v[220:221], s[24:25], 0, v[128:129]
	s_addc_u32 s93, s25, 0
	s_add_i32 s91, s84, s30
	global_load_lds_dwordx4 v[220:221], off
	v_lshl_add_u64 v[222:223], s[92:93], 0, v[132:133]
	s_mov_b32 m0, s91
	v_lshl_add_u64 v[224:225], s[26:27], 0, v[130:131]
	global_load_lds_dwordx4 v[222:223], off
	v_lshl_add_u64 v[222:223], s[92:93], 0, v[128:129]
	s_add_i32 m0, s91, 0x2000
	s_nop 0
	global_load_lds_dwordx4 v[222:223], off
	v_lshl_add_u64 v[222:223], s[26:27], 0, v[134:135]
	s_mov_b32 m0, s21
	s_nop 0
	global_load_lds_dwordx4 v[222:223], off
	s_mov_b32 m0, s35
	s_nop 0
	global_load_lds_dwordx4 v[224:225], off
	s_waitcnt vmcnt(8)
	s_waitcnt lgkmcnt(0)
	s_setprio 1
	s_barrier
	v_mfma_f32_16x16x32_bf16 v[60:63], v[144:147], v[184:187], 0
	v_mfma_f32_16x16x32_bf16 v[56:59], v[160:163], v[184:187], 0
	v_mfma_f32_16x16x32_bf16 v[44:47], v[144:147], v[192:195], 0
	v_mfma_f32_16x16x32_bf16 v[40:43], v[160:163], v[192:195], 0
	v_mfma_f32_16x16x32_bf16 v[28:31], v[144:147], v[200:203], 0
	v_mfma_f32_16x16x32_bf16 v[24:27], v[160:163], v[200:203], 0
	v_mfma_f32_16x16x32_bf16 v[12:15], v[144:147], v[212:215], 0
	v_mfma_f32_16x16x32_bf16 v[8:11], v[160:163], v[212:215], 0
	v_mfma_f32_16x16x32_bf16 v[60:63], v[156:159], v[188:191], v[60:63]
	v_mfma_f32_16x16x32_bf16 v[56:59], v[164:167], v[188:191], v[56:59]
	v_mfma_f32_16x16x32_bf16 v[44:47], v[156:159], v[196:199], v[44:47]
	v_mfma_f32_16x16x32_bf16 v[40:43], v[164:167], v[196:199], v[40:43]
	v_mfma_f32_16x16x32_bf16 v[28:31], v[156:159], v[208:211], v[28:31]
	v_mfma_f32_16x16x32_bf16 v[24:27], v[164:167], v[208:211], v[24:27]
	v_mfma_f32_16x16x32_bf16 v[12:15], v[156:159], v[216:219], v[12:15]
	v_mfma_f32_16x16x32_bf16 v[8:11], v[164:167], v[216:219], v[8:11]
	s_setprio 0
	s_setprio 1
	v_mfma_f32_16x16x32_bf16 v[52:55], v[168:171], v[184:187], 0
	v_mfma_f32_16x16x32_bf16 v[48:51], v[176:179], v[184:187], 0
	v_mfma_f32_16x16x32_bf16 v[36:39], v[168:171], v[192:195], 0
	v_mfma_f32_16x16x32_bf16 v[32:35], v[176:179], v[192:195], 0
	v_mfma_f32_16x16x32_bf16 v[20:23], v[168:171], v[200:203], 0
	v_mfma_f32_16x16x32_bf16 v[16:19], v[176:179], v[200:203], 0
	v_mfma_f32_16x16x32_bf16 v[4:7], v[168:171], v[212:215], 0
	v_mfma_f32_16x16x32_bf16 v[0:3], v[176:179], v[212:215], 0
	v_mfma_f32_16x16x32_bf16 v[52:55], v[172:175], v[188:191], v[52:55]
	v_mfma_f32_16x16x32_bf16 v[48:51], v[180:183], v[188:191], v[48:51]
	v_mfma_f32_16x16x32_bf16 v[36:39], v[172:175], v[196:199], v[36:39]
	v_mfma_f32_16x16x32_bf16 v[32:35], v[180:183], v[196:199], v[32:35]
	v_mfma_f32_16x16x32_bf16 v[20:23], v[172:175], v[208:211], v[20:23]
	v_mfma_f32_16x16x32_bf16 v[16:19], v[180:183], v[208:211], v[16:19]
	v_mfma_f32_16x16x32_bf16 v[4:7], v[172:175], v[216:219], v[4:7]
	v_mfma_f32_16x16x32_bf16 v[0:3], v[180:183], v[216:219], v[0:3]
	s_barrier
	s_setprio 0
	s_add_i32 s91, 0, 0x18000
	s_add_i32 s92, 0, 0x1c000
	v_add_u32_e32 v164, s91, v149
	v_add_u32_e32 v180, s92, v149
	ds_read_b128 v[144:147], v164
	ds_read_b128 v[156:159], v164 offset:1024
	ds_read_b128 v[160:163], v164 offset:2048
	ds_read_b128 v[164:167], v164 offset:3072
	ds_read_b128 v[168:171], v180
	ds_read_b128 v[172:175], v180 offset:1024
	ds_read_b128 v[176:179], v180 offset:2048
	ds_read_b128 v[180:183], v180 offset:3072
	s_add_u32 s26, s26, 0x40000
	s_addc_u32 s27, s27, 0
	s_mov_b32 m0, s36
	v_lshl_add_u64 v[226:227], s[26:27], 0, v[134:135]
	ds_read_b128 v[184:187], v153 offset:32768
	ds_read_b128 v[188:191], v153 offset:33792
	ds_read_b128 v[192:195], v153 offset:34816
	ds_read_b128 v[196:199], v153 offset:35840
	ds_read_b128 v[200:203], v153 offset:36864
	ds_read_b128 v[208:211], v153 offset:37888
	ds_read_b128 v[212:215], v153 offset:38912
	ds_read_b128 v[216:219], v153 offset:39936
	global_load_lds_dwordx4 v[226:227], off
	v_lshl_add_u64 v[226:227], s[26:27], 0, v[130:131]
	s_mov_b32 m0, s37
	s_nop 0
	global_load_lds_dwordx4 v[226:227], off
	s_waitcnt vmcnt(8)
	s_waitcnt lgkmcnt(0)
	s_setprio 1
	s_barrier
	v_mfma_f32_16x16x32_bf16 v[124:127], v[144:147], v[184:187], v[124:127]
	v_mfma_f32_16x16x32_bf16 v[120:123], v[160:163], v[184:187], v[120:123]
	v_mfma_f32_16x16x32_bf16 v[116:119], v[144:147], v[192:195], v[116:119]
	v_mfma_f32_16x16x32_bf16 v[112:115], v[160:163], v[192:195], v[112:115]
	v_mfma_f32_16x16x32_bf16 v[104:107], v[144:147], v[200:203], v[104:107]
	v_mfma_f32_16x16x32_bf16 v[96:99], v[160:163], v[200:203], v[96:99]
	v_mfma_f32_16x16x32_bf16 v[76:79], v[144:147], v[212:215], v[76:79]
	v_mfma_f32_16x16x32_bf16 v[72:75], v[160:163], v[212:215], v[72:75]
	v_mfma_f32_16x16x32_bf16 v[124:127], v[156:159], v[188:191], v[124:127]
	v_mfma_f32_16x16x32_bf16 v[120:123], v[164:167], v[188:191], v[120:123]
	v_mfma_f32_16x16x32_bf16 v[116:119], v[156:159], v[196:199], v[116:119]
	v_mfma_f32_16x16x32_bf16 v[112:115], v[164:167], v[196:199], v[112:115]
	v_mfma_f32_16x16x32_bf16 v[104:107], v[156:159], v[208:211], v[104:107]
	v_mfma_f32_16x16x32_bf16 v[96:99], v[164:167], v[208:211], v[96:99]
	v_mfma_f32_16x16x32_bf16 v[76:79], v[156:159], v[216:219], v[76:79]
	v_mfma_f32_16x16x32_bf16 v[72:75], v[164:167], v[216:219], v[72:75]
	s_setprio 0
	s_setprio 1
	v_mfma_f32_16x16x32_bf16 v[108:111], v[168:171], v[184:187], v[108:111]
	v_mfma_f32_16x16x32_bf16 v[100:103], v[176:179], v[184:187], v[100:103]
	v_mfma_f32_16x16x32_bf16 v[92:95], v[168:171], v[192:195], v[92:95]
	v_mfma_f32_16x16x32_bf16 v[88:91], v[176:179], v[192:195], v[88:91]
	v_mfma_f32_16x16x32_bf16 v[84:87], v[168:171], v[200:203], v[84:87]
	v_mfma_f32_16x16x32_bf16 v[80:83], v[176:179], v[200:203], v[80:83]
	v_mfma_f32_16x16x32_bf16 v[68:71], v[168:171], v[212:215], v[68:71]
	v_mfma_f32_16x16x32_bf16 v[64:67], v[176:179], v[212:215], v[64:67]
	v_mfma_f32_16x16x32_bf16 v[108:111], v[172:175], v[188:191], v[108:111]
	v_mfma_f32_16x16x32_bf16 v[100:103], v[180:183], v[188:191], v[100:103]
	v_mfma_f32_16x16x32_bf16 v[92:95], v[172:175], v[196:199], v[92:95]
	v_mfma_f32_16x16x32_bf16 v[88:91], v[180:183], v[196:199], v[88:91]
	v_mfma_f32_16x16x32_bf16 v[84:87], v[172:175], v[208:211], v[84:87]
	v_mfma_f32_16x16x32_bf16 v[80:83], v[180:183], v[208:211], v[80:83]
	v_mfma_f32_16x16x32_bf16 v[68:71], v[172:175], v[216:219], v[68:71]
	v_mfma_f32_16x16x32_bf16 v[64:67], v[180:183], v[216:219], v[64:67]
	s_barrier
	s_setprio 0
	s_add_i32 s26, s91, s30
	v_lshl_add_u64 v[204:205], v[204:205], 0, s[8:9]
	s_mov_b32 m0, s26
	ds_read_b128 v[184:187], v153 offset:49152
	ds_read_b128 v[188:191], v153 offset:50176
	ds_read_b128 v[192:195], v153 offset:51200
	ds_read_b128 v[196:199], v153 offset:52224
	ds_read_b128 v[200:203], v153 offset:53248
	ds_read_b128 v[208:211], v153 offset:54272
	ds_read_b128 v[212:215], v153 offset:55296
	ds_read_b128 v[216:219], v153 offset:56320
	global_load_lds_dwordx4 v[204:205], off
	s_add_i32 m0, s26, 0x2000
	s_add_u32 s24, s24, 0x40080
	v_lshl_add_u64 v[204:205], v[220:221], 0, s[8:9]
	s_addc_u32 s25, s25, 0
	s_add_i32 s26, s92, s30
	global_load_lds_dwordx4 v[204:205], off
	v_lshl_add_u64 v[204:205], s[24:25], 0, v[132:133]
	s_mov_b32 m0, s26
	s_nop 0
	global_load_lds_dwordx4 v[204:205], off
	v_lshl_add_u64 v[204:205], s[24:25], 0, v[128:129]
	s_add_i32 m0, s26, 0x2000
	s_nop 0
	global_load_lds_dwordx4 v[204:205], off
	v_lshl_add_u64 v[204:205], v[222:223], 0, s[8:9]
	s_mov_b32 m0, s76
	s_nop 0
	global_load_lds_dwordx4 v[204:205], off
	v_lshl_add_u64 v[204:205], v[224:225], 0, s[8:9]
	s_mov_b32 m0, s77
	s_nop 0
	global_load_lds_dwordx4 v[204:205], off
	s_waitcnt vmcnt(8)
	s_waitcnt lgkmcnt(0)
	s_setprio 1
	s_barrier
	v_mfma_f32_16x16x32_bf16 v[60:63], v[144:147], v[184:187], v[60:63]
	v_mfma_f32_16x16x32_bf16 v[56:59], v[160:163], v[184:187], v[56:59]
	v_mfma_f32_16x16x32_bf16 v[44:47], v[144:147], v[192:195], v[44:47]
	v_mfma_f32_16x16x32_bf16 v[40:43], v[160:163], v[192:195], v[40:43]
	v_mfma_f32_16x16x32_bf16 v[28:31], v[144:147], v[200:203], v[28:31]
	v_mfma_f32_16x16x32_bf16 v[24:27], v[160:163], v[200:203], v[24:27]
	v_mfma_f32_16x16x32_bf16 v[12:15], v[144:147], v[212:215], v[12:15]
	v_mfma_f32_16x16x32_bf16 v[8:11], v[160:163], v[212:215], v[8:11]
	v_mfma_f32_16x16x32_bf16 v[60:63], v[156:159], v[188:191], v[60:63]
	v_mfma_f32_16x16x32_bf16 v[56:59], v[164:167], v[188:191], v[56:59]
	v_mfma_f32_16x16x32_bf16 v[44:47], v[156:159], v[196:199], v[44:47]
	v_mfma_f32_16x16x32_bf16 v[40:43], v[164:167], v[196:199], v[40:43]
	v_mfma_f32_16x16x32_bf16 v[28:31], v[156:159], v[208:211], v[28:31]
	v_mfma_f32_16x16x32_bf16 v[24:27], v[164:167], v[208:211], v[24:27]
	v_mfma_f32_16x16x32_bf16 v[12:15], v[156:159], v[216:219], v[12:15]
	v_mfma_f32_16x16x32_bf16 v[8:11], v[164:167], v[216:219], v[8:11]
	s_setprio 0
	s_setprio 1
	v_mfma_f32_16x16x32_bf16 v[52:55], v[168:171], v[184:187], v[52:55]
	v_mfma_f32_16x16x32_bf16 v[48:51], v[176:179], v[184:187], v[48:51]
	v_mfma_f32_16x16x32_bf16 v[36:39], v[168:171], v[192:195], v[36:39]
	v_mfma_f32_16x16x32_bf16 v[32:35], v[176:179], v[192:195], v[32:35]
	v_mfma_f32_16x16x32_bf16 v[20:23], v[168:171], v[200:203], v[20:23]
	v_mfma_f32_16x16x32_bf16 v[16:19], v[176:179], v[200:203], v[16:19]
	v_mfma_f32_16x16x32_bf16 v[4:7], v[168:171], v[212:215], v[4:7]
	v_mfma_f32_16x16x32_bf16 v[0:3], v[176:179], v[212:215], v[0:3]
	v_mfma_f32_16x16x32_bf16 v[52:55], v[172:175], v[188:191], v[52:55]
	v_mfma_f32_16x16x32_bf16 v[48:51], v[180:183], v[188:191], v[48:51]
	v_mfma_f32_16x16x32_bf16 v[36:39], v[172:175], v[196:199], v[36:39]
	v_mfma_f32_16x16x32_bf16 v[32:35], v[180:183], v[196:199], v[32:35]
	v_mfma_f32_16x16x32_bf16 v[20:23], v[172:175], v[208:211], v[20:23]
	v_mfma_f32_16x16x32_bf16 v[16:19], v[180:183], v[208:211], v[16:19]
	v_mfma_f32_16x16x32_bf16 v[4:7], v[172:175], v[216:219], v[4:7]
	v_mfma_f32_16x16x32_bf16 v[0:3], v[180:183], v[216:219], v[0:3]
	s_barrier
	s_setprio 0
	s_add_i32 s90, s90, 2
	s_add_u32 s22, s22, 0x100
	s_addc_u32 s23, s23, 0
	s_add_u32 s88, s88, 0x100
	s_addc_u32 s89, s89, 0
	s_cmp_gt_u32 s90, 13

.LBB0_198:
	s_ashr_i32 s15, s14, 31
	s_lshl_b64 s[16:17], s[14:15], 19
	s_add_u32 s16, s31, s16
	s_addc_u32 s17, s34, s17
	s_and_b64 s[18:19], s[0:1], exec
	s_cselect_b32 s15, s17, s23
	s_cselect_b32 s88, s16, s22
	s_ashr_i32 s13, s12, 31
	s_lshl_b64 s[18:19], s[12:13], 19
	s_add_u32 s18, s82, s18
	s_addc_u32 s19, s83, s19
	s_and_b64 s[26:27], s[0:1], exec
	s_cselect_b32 s13, s19, s25
	s_cselect_b32 s89, s18, s24
	s_add_u32 s22, s22, 0x40080
	s_addc_u32 s23, s23, 0
	s_add_u32 s90, s24, 0x100
	s_addc_u32 s91, s25, 0
	s_mov_b32 s92, -2
	s_nop 0
	s_nop 0
	s_nop 0
	s_nop 0
	s_nop 0
	s_nop 0
	s_nop 0
	s_nop 0
	s_nop 0
	s_nop 0
	s_nop 0
	s_nop 0
	s_nop 0
	s_nop 0
	s_nop 0
	ds_read_b128 v[144:147], v167
	ds_read_b128 v[148:151], v167 offset:1024
	ds_read_b128 v[152:155], v167 offset:2048
	ds_read_b128 v[156:159], v167 offset:3072
	ds_read_b128 v[160:163], v168
	ds_read_b128 v[172:175], v168 offset:1024
	ds_read_b128 v[176:179], v168 offset:2048
	ds_read_b128 v[180:183], v168 offset:3072
	s_add_u32 s24, s22, 0xfffc0080
	s_addc_u32 s25, s23, -1
	s_cmp_eq_u32 s92, 12
	s_cselect_b32 s27, s15, s25
	s_cselect_b32 s26, s88, s24
	s_cselect_b32 s25, s13, s91
	s_cselect_b32 s24, s89, s90
	v_lshl_add_u64 v[204:205], s[22:23], 0, v[136:137]
	s_add_i32 m0, s21, 0xc000
	ds_read_b128 v[184:187], v169
	ds_read_b128 v[188:191], v169 offset:1024
	ds_read_b128 v[192:195], v169 offset:2048
	ds_read_b128 v[196:199], v169 offset:3072
	ds_read_b128 v[200:203], v169 offset:4096
	ds_read_b128 v[208:211], v169 offset:5120
	ds_read_b128 v[212:215], v169 offset:6144
	ds_read_b128 v[216:219], v169 offset:7168
	global_load_lds_dwordx4 v[204:205], off
	v_lshl_add_u64 v[204:205], s[22:23], 0, v[138:139]
	s_add_i32 m0, s21, 0xe000
	s_nop 0
	global_load_lds_dwordx4 v[204:205], off
	s_waitcnt vmcnt(8)
	s_waitcnt lgkmcnt(0)
	s_setprio 1
	s_barrier
	v_mfma_f32_16x16x32_bf16 v[124:127], v[144:147], v[184:187], 0
	v_mfma_f32_16x16x32_bf16 v[120:123], v[152:155], v[184:187], 0
	v_mfma_f32_16x16x32_bf16 v[116:119], v[144:147], v[192:195], 0
	v_mfma_f32_16x16x32_bf16 v[112:115], v[152:155], v[192:195], 0
	v_mfma_f32_16x16x32_bf16 v[108:111], v[144:147], v[200:203], 0
	v_mfma_f32_16x16x32_bf16 v[88:91], v[152:155], v[200:203], 0
	v_mfma_f32_16x16x32_bf16 v[80:83], v[144:147], v[212:215], 0
	v_mfma_f32_16x16x32_bf16 v[72:75], v[152:155], v[212:215], 0
	v_mfma_f32_16x16x32_bf16 v[124:127], v[148:151], v[188:191], v[124:127]
	v_mfma_f32_16x16x32_bf16 v[120:123], v[156:159], v[188:191], v[120:123]
	v_mfma_f32_16x16x32_bf16 v[116:119], v[148:151], v[196:199], v[116:119]
	v_mfma_f32_16x16x32_bf16 v[112:115], v[156:159], v[196:199], v[112:115]
	v_mfma_f32_16x16x32_bf16 v[108:111], v[148:151], v[208:211], v[108:111]
	v_mfma_f32_16x16x32_bf16 v[88:91], v[156:159], v[208:211], v[88:91]
	v_mfma_f32_16x16x32_bf16 v[80:83], v[148:151], v[216:219], v[80:83]
	v_mfma_f32_16x16x32_bf16 v[72:75], v[156:159], v[216:219], v[72:75]
	s_setprio 0
	s_setprio 1
	v_mfma_f32_16x16x32_bf16 v[104:107], v[160:163], v[184:187], 0
	v_mfma_f32_16x16x32_bf16 v[100:103], v[176:179], v[184:187], 0
	v_mfma_f32_16x16x32_bf16 v[96:99], v[160:163], v[192:195], 0
	v_mfma_f32_16x16x32_bf16 v[92:95], v[176:179], v[192:195], 0
	v_mfma_f32_16x16x32_bf16 v[84:87], v[160:163], v[200:203], 0
	v_mfma_f32_16x16x32_bf16 v[76:79], v[176:179], v[200:203], 0
	v_mfma_f32_16x16x32_bf16 v[68:71], v[160:163], v[212:215], 0
	v_mfma_f32_16x16x32_bf16 v[64:67], v[176:179], v[212:215], 0
	v_mfma_f32_16x16x32_bf16 v[104:107], v[172:175], v[188:191], v[104:107]
	v_mfma_f32_16x16x32_bf16 v[100:103], v[180:183], v[188:191], v[100:103]
	v_mfma_f32_16x16x32_bf16 v[96:99], v[172:175], v[196:199], v[96:99]
	v_mfma_f32_16x16x32_bf16 v[92:95], v[180:183], v[196:199], v[92:95]
	v_mfma_f32_16x16x32_bf16 v[84:87], v[172:175], v[208:211], v[84:87]
	v_mfma_f32_16x16x32_bf16 v[76:79], v[180:183], v[208:211], v[76:79]
	v_mfma_f32_16x16x32_bf16 v[68:71], v[172:175], v[216:219], v[68:71]
	v_mfma_f32_16x16x32_bf16 v[64:67], v[180:183], v[216:219], v[64:67]
	s_barrier
	s_setprio 0
	s_add_i32 s93, s84, s35
	v_lshl_add_u64 v[204:205], s[24:25], 0, v[130:131]
	s_mov_b32 m0, s93
	ds_read_b128 v[184:187], v169 offset:16384
	ds_read_b128 v[188:191], v169 offset:17408
	ds_read_b128 v[192:195], v169 offset:18432
	ds_read_b128 v[196:199], v169 offset:19456
	ds_read_b128 v[200:203], v169 offset:20480
	ds_read_b128 v[208:211], v169 offset:21504
	ds_read_b128 v[212:215], v169 offset:22528
	ds_read_b128 v[216:219], v169 offset:23552
	global_load_lds_dwordx4 v[204:205], off
	s_add_i32 m0, s93, 0x2000
	s_add_u32 s94, s24, 0x40000
	v_lshl_add_u64 v[220:221], s[24:25], 0, v[134:135]
	s_addc_u32 s95, s25, 0
	s_add_i32 s93, s85, s35
	global_load_lds_dwordx4 v[220:221], off
	v_lshl_add_u64 v[222:223], s[94:95], 0, v[130:131]
	s_mov_b32 m0, s93
	v_lshl_add_u64 v[224:225], s[26:27], 0, v[132:133]
	global_load_lds_dwordx4 v[222:223], off
	v_lshl_add_u64 v[222:223], s[94:95], 0, v[134:135]
	s_add_i32 m0, s93, 0x2000
	s_nop 0
	global_load_lds_dwordx4 v[222:223], off
	v_lshl_add_u64 v[222:223], s[26:27], 0, v[128:129]
	s_mov_b32 m0, s21
	s_nop 0
	global_load_lds_dwordx4 v[222:223], off
	s_mov_b32 m0, s36
	s_nop 0
	global_load_lds_dwordx4 v[224:225], off
	s_waitcnt vmcnt(8)
	s_waitcnt lgkmcnt(0)
	s_setprio 1
	s_barrier
	v_mfma_f32_16x16x32_bf16 v[60:63], v[144:147], v[184:187], 0
	v_mfma_f32_16x16x32_bf16 v[56:59], v[152:155], v[184:187], 0
	v_mfma_f32_16x16x32_bf16 v[48:51], v[144:147], v[192:195], 0
	v_mfma_f32_16x16x32_bf16 v[40:43], v[152:155], v[192:195], 0
	v_mfma_f32_16x16x32_bf16 v[32:35], v[144:147], v[200:203], 0
	v_mfma_f32_16x16x32_bf16 v[24:27], v[152:155], v[200:203], 0
	v_mfma_f32_16x16x32_bf16 v[16:19], v[144:147], v[212:215], 0
	v_mfma_f32_16x16x32_bf16 v[8:11], v[152:155], v[212:215], 0
	v_mfma_f32_16x16x32_bf16 v[60:63], v[148:151], v[188:191], v[60:63]
	v_mfma_f32_16x16x32_bf16 v[56:59], v[156:159], v[188:191], v[56:59]
	v_mfma_f32_16x16x32_bf16 v[48:51], v[148:151], v[196:199], v[48:51]
	v_mfma_f32_16x16x32_bf16 v[40:43], v[156:159], v[196:199], v[40:43]
	v_mfma_f32_16x16x32_bf16 v[32:35], v[148:151], v[208:211], v[32:35]
	v_mfma_f32_16x16x32_bf16 v[24:27], v[156:159], v[208:211], v[24:27]
	v_mfma_f32_16x16x32_bf16 v[16:19], v[148:151], v[216:219], v[16:19]
	v_mfma_f32_16x16x32_bf16 v[8:11], v[156:159], v[216:219], v[8:11]
	s_setprio 0
	s_setprio 1
	v_mfma_f32_16x16x32_bf16 v[52:55], v[160:163], v[184:187], 0
	v_mfma_f32_16x16x32_bf16 v[44:47], v[176:179], v[184:187], 0
	v_mfma_f32_16x16x32_bf16 v[36:39], v[160:163], v[192:195], 0
	v_mfma_f32_16x16x32_bf16 v[28:31], v[176:179], v[192:195], 0
	v_mfma_f32_16x16x32_bf16 v[20:23], v[160:163], v[200:203], 0
	v_mfma_f32_16x16x32_bf16 v[12:15], v[176:179], v[200:203], 0
	v_mfma_f32_16x16x32_bf16 v[4:7], v[160:163], v[212:215], 0
	v_mfma_f32_16x16x32_bf16 v[0:3], v[176:179], v[212:215], 0
	v_mfma_f32_16x16x32_bf16 v[52:55], v[172:175], v[188:191], v[52:55]
	v_mfma_f32_16x16x32_bf16 v[44:47], v[180:183], v[188:191], v[44:47]
	v_mfma_f32_16x16x32_bf16 v[36:39], v[172:175], v[196:199], v[36:39]
	v_mfma_f32_16x16x32_bf16 v[28:31], v[180:183], v[196:199], v[28:31]
	v_mfma_f32_16x16x32_bf16 v[20:23], v[172:175], v[208:211], v[20:23]
	v_mfma_f32_16x16x32_bf16 v[12:15], v[180:183], v[208:211], v[12:15]
	v_mfma_f32_16x16x32_bf16 v[4:7], v[172:175], v[216:219], v[4:7]
	v_mfma_f32_16x16x32_bf16 v[0:3], v[180:183], v[216:219], v[0:3]
	s_barrier
	s_setprio 0
	s_add_i32 s93, 0, 0x18000
	s_add_i32 s94, 0, 0x1c000
	v_add_u32_e32 v156, s93, v165
	v_add_u32_e32 v171, s94, v165
	ds_read_b128 v[144:147], v156
	ds_read_b128 v[148:151], v156 offset:1024
	ds_read_b128 v[152:155], v156 offset:2048
	ds_read_b128 v[156:159], v156 offset:3072
	ds_read_b128 v[160:163], v171
	ds_read_b128 v[172:175], v171 offset:1024
	ds_read_b128 v[176:179], v171 offset:2048
	ds_read_b128 v[180:183], v171 offset:3072
	s_add_u32 s26, s26, 0x40000
	s_addc_u32 s27, s27, 0
	s_mov_b32 m0, s37
	v_lshl_add_u64 v[226:227], s[26:27], 0, v[128:129]
	ds_read_b128 v[184:187], v169 offset:32768
	ds_read_b128 v[188:191], v169 offset:33792
	ds_read_b128 v[192:195], v169 offset:34816
	ds_read_b128 v[196:199], v169 offset:35840
	ds_read_b128 v[200:203], v169 offset:36864
	ds_read_b128 v[208:211], v169 offset:37888
	ds_read_b128 v[212:215], v169 offset:38912
	ds_read_b128 v[216:219], v169 offset:39936
	global_load_lds_dwordx4 v[226:227], off
	v_lshl_add_u64 v[226:227], s[26:27], 0, v[132:133]
	s_mov_b32 m0, s39
	s_nop 0
	global_load_lds_dwordx4 v[226:227], off
	s_waitcnt vmcnt(8)
	s_waitcnt lgkmcnt(0)
	s_setprio 1
	s_barrier
	v_mfma_f32_16x16x32_bf16 v[124:127], v[144:147], v[184:187], v[124:127]
	v_mfma_f32_16x16x32_bf16 v[120:123], v[152:155], v[184:187], v[120:123]
	v_mfma_f32_16x16x32_bf16 v[116:119], v[144:147], v[192:195], v[116:119]
	v_mfma_f32_16x16x32_bf16 v[112:115], v[152:155], v[192:195], v[112:115]
	v_mfma_f32_16x16x32_bf16 v[108:111], v[144:147], v[200:203], v[108:111]
	v_mfma_f32_16x16x32_bf16 v[88:91], v[152:155], v[200:203], v[88:91]
	v_mfma_f32_16x16x32_bf16 v[80:83], v[144:147], v[212:215], v[80:83]
	v_mfma_f32_16x16x32_bf16 v[72:75], v[152:155], v[212:215], v[72:75]
	v_mfma_f32_16x16x32_bf16 v[124:127], v[148:151], v[188:191], v[124:127]
	v_mfma_f32_16x16x32_bf16 v[120:123], v[156:159], v[188:191], v[120:123]
	v_mfma_f32_16x16x32_bf16 v[116:119], v[148:151], v[196:199], v[116:119]
	v_mfma_f32_16x16x32_bf16 v[112:115], v[156:159], v[196:199], v[112:115]
	v_mfma_f32_16x16x32_bf16 v[108:111], v[148:151], v[208:211], v[108:111]
	v_mfma_f32_16x16x32_bf16 v[88:91], v[156:159], v[208:211], v[88:91]
	v_mfma_f32_16x16x32_bf16 v[80:83], v[148:151], v[216:219], v[80:83]
	v_mfma_f32_16x16x32_bf16 v[72:75], v[156:159], v[216:219], v[72:75]
	s_setprio 0
	s_setprio 1
	v_mfma_f32_16x16x32_bf16 v[104:107], v[160:163], v[184:187], v[104:107]
	v_mfma_f32_16x16x32_bf16 v[100:103], v[176:179], v[184:187], v[100:103]
	v_mfma_f32_16x16x32_bf16 v[96:99], v[160:163], v[192:195], v[96:99]
	v_mfma_f32_16x16x32_bf16 v[92:95], v[176:179], v[192:195], v[92:95]
	v_mfma_f32_16x16x32_bf16 v[84:87], v[160:163], v[200:203], v[84:87]
	v_mfma_f32_16x16x32_bf16 v[76:79], v[176:179], v[200:203], v[76:79]
	v_mfma_f32_16x16x32_bf16 v[68:71], v[160:163], v[212:215], v[68:71]
	v_mfma_f32_16x16x32_bf16 v[64:67], v[176:179], v[212:215], v[64:67]
	v_mfma_f32_16x16x32_bf16 v[104:107], v[172:175], v[188:191], v[104:107]
	v_mfma_f32_16x16x32_bf16 v[100:103], v[180:183], v[188:191], v[100:103]
	v_mfma_f32_16x16x32_bf16 v[96:99], v[172:175], v[196:199], v[96:99]
	v_mfma_f32_16x16x32_bf16 v[92:95], v[180:183], v[196:199], v[92:95]
	v_mfma_f32_16x16x32_bf16 v[84:87], v[172:175], v[208:211], v[84:87]
	v_mfma_f32_16x16x32_bf16 v[76:79], v[180:183], v[208:211], v[76:79]
	v_mfma_f32_16x16x32_bf16 v[68:71], v[172:175], v[216:219], v[68:71]
	v_mfma_f32_16x16x32_bf16 v[64:67], v[180:183], v[216:219], v[64:67]
	s_barrier
	s_setprio 0
	s_add_i32 s26, s93, s35
	v_lshl_add_u64 v[204:205], v[204:205], 0, s[8:9]
	s_mov_b32 m0, s26
	ds_read_b128 v[184:187], v169 offset:49152
	ds_read_b128 v[188:191], v169 offset:50176
	ds_read_b128 v[192:195], v169 offset:51200
	ds_read_b128 v[196:199], v169 offset:52224
	ds_read_b128 v[200:203], v169 offset:53248
	ds_read_b128 v[208:211], v169 offset:54272
	ds_read_b128 v[212:215], v169 offset:55296
	ds_read_b128 v[216:219], v169 offset:56320
	global_load_lds_dwordx4 v[204:205], off
	s_add_i32 m0, s26, 0x2000
	s_add_u32 s24, s24, 0x40080
	v_lshl_add_u64 v[204:205], v[220:221], 0, s[8:9]
	s_addc_u32 s25, s25, 0
	s_add_i32 s26, s94, s35
	global_load_lds_dwordx4 v[204:205], off
	v_lshl_add_u64 v[204:205], s[24:25], 0, v[130:131]
	s_mov_b32 m0, s26
	s_nop 0
	global_load_lds_dwordx4 v[204:205], off
	v_lshl_add_u64 v[204:205], s[24:25], 0, v[134:135]
	s_add_i32 m0, s26, 0x2000
	s_nop 0
	global_load_lds_dwordx4 v[204:205], off
	v_lshl_add_u64 v[204:205], v[222:223], 0, s[8:9]
	s_mov_b32 m0, s77
	s_nop 0
	global_load_lds_dwordx4 v[204:205], off
	v_lshl_add_u64 v[204:205], v[224:225], 0, s[8:9]
	s_mov_b32 m0, s78
	s_nop 0
	global_load_lds_dwordx4 v[204:205], off
	s_waitcnt vmcnt(8)
	s_waitcnt lgkmcnt(0)
	s_setprio 1
	s_barrier
	v_mfma_f32_16x16x32_bf16 v[60:63], v[144:147], v[184:187], v[60:63]
	v_mfma_f32_16x16x32_bf16 v[56:59], v[152:155], v[184:187], v[56:59]
	v_mfma_f32_16x16x32_bf16 v[48:51], v[144:147], v[192:195], v[48:51]
	v_mfma_f32_16x16x32_bf16 v[40:43], v[152:155], v[192:195], v[40:43]
	v_mfma_f32_16x16x32_bf16 v[32:35], v[144:147], v[200:203], v[32:35]
	v_mfma_f32_16x16x32_bf16 v[24:27], v[152:155], v[200:203], v[24:27]
	v_mfma_f32_16x16x32_bf16 v[16:19], v[144:147], v[212:215], v[16:19]
	v_mfma_f32_16x16x32_bf16 v[8:11], v[152:155], v[212:215], v[8:11]
	v_mfma_f32_16x16x32_bf16 v[60:63], v[148:151], v[188:191], v[60:63]
	v_mfma_f32_16x16x32_bf16 v[56:59], v[156:159], v[188:191], v[56:59]
	v_mfma_f32_16x16x32_bf16 v[48:51], v[148:151], v[196:199], v[48:51]
	v_mfma_f32_16x16x32_bf16 v[40:43], v[156:159], v[196:199], v[40:43]
	v_mfma_f32_16x16x32_bf16 v[32:35], v[148:151], v[208:211], v[32:35]
	v_mfma_f32_16x16x32_bf16 v[24:27], v[156:159], v[208:211], v[24:27]
	v_mfma_f32_16x16x32_bf16 v[16:19], v[148:151], v[216:219], v[16:19]
	v_mfma_f32_16x16x32_bf16 v[8:11], v[156:159], v[216:219], v[8:11]
	s_setprio 0
	s_setprio 1
	v_mfma_f32_16x16x32_bf16 v[52:55], v[160:163], v[184:187], v[52:55]
	v_mfma_f32_16x16x32_bf16 v[44:47], v[176:179], v[184:187], v[44:47]
	v_mfma_f32_16x16x32_bf16 v[36:39], v[160:163], v[192:195], v[36:39]
	v_mfma_f32_16x16x32_bf16 v[28:31], v[176:179], v[192:195], v[28:31]
	v_mfma_f32_16x16x32_bf16 v[20:23], v[160:163], v[200:203], v[20:23]
	v_mfma_f32_16x16x32_bf16 v[12:15], v[176:179], v[200:203], v[12:15]
	v_mfma_f32_16x16x32_bf16 v[4:7], v[160:163], v[212:215], v[4:7]
	v_mfma_f32_16x16x32_bf16 v[0:3], v[176:179], v[212:215], v[0:3]
	v_mfma_f32_16x16x32_bf16 v[52:55], v[172:175], v[188:191], v[52:55]
	v_mfma_f32_16x16x32_bf16 v[44:47], v[180:183], v[188:191], v[44:47]
	v_mfma_f32_16x16x32_bf16 v[36:39], v[172:175], v[196:199], v[36:39]
	v_mfma_f32_16x16x32_bf16 v[28:31], v[180:183], v[196:199], v[28:31]
	v_mfma_f32_16x16x32_bf16 v[20:23], v[172:175], v[208:211], v[20:23]
	v_mfma_f32_16x16x32_bf16 v[12:15], v[180:183], v[208:211], v[12:15]
	v_mfma_f32_16x16x32_bf16 v[4:7], v[172:175], v[216:219], v[4:7]
	v_mfma_f32_16x16x32_bf16 v[0:3], v[180:183], v[216:219], v[0:3]
	s_barrier
	s_setprio 0
	s_add_i32 s92, s92, 2
	s_add_u32 s22, s22, 0x100
	s_addc_u32 s23, s23, 0
	s_add_u32 s90, s90, 0x100
	s_addc_u32 s91, s91, 0
	s_cmp_gt_u32 s92, 13

.LBB0_521:
	s_ashr_i32 s17, s16, 31
	s_lshl_b64 s[18:19], s[16:17], 19
	s_add_u32 s18, s84, s18
	s_addc_u32 s19, s85, s19
	s_and_b64 s[20:21], s[4:5], exec
	s_cselect_b32 s3, s19, s27
	s_cselect_b32 s17, s18, s26
	s_ashr_i32 s15, s14, 31
	s_lshl_b64 s[20:21], s[14:15], 19
	s_add_u32 s20, s39, s20
	s_addc_u32 s21, s50, s21
	s_and_b64 s[30:31], s[4:5], exec
	s_cselect_b32 s15, s21, s29
	s_cselect_b32 s23, s20, s28
	s_add_u32 s92, s28, 0x100
	s_addc_u32 s93, s29, 0
	s_mov_b32 s94, -2
	s_waitcnt lgkmcnt(0)
	s_nop 0
	ds_read_b128 v[128:131], v203
	ds_read_b128 v[132:135], v203 offset:1024
	ds_read_b128 v[136:139], v203 offset:2048
	ds_read_b128 v[140:143], v203 offset:3072
	ds_read_b128 v[144:147], v204
	ds_read_b128 v[148:151], v204 offset:1024
	ds_read_b128 v[152:155], v204 offset:2048
	ds_read_b128 v[156:159], v204 offset:3072
	s_add_u32 s28, s26, 0x100
	s_addc_u32 s29, s27, 0
	s_cmp_eq_u32 s94, 12
	s_cselect_b32 s35, s3, s29
	s_cselect_b32 s34, s17, s28
	s_cselect_b32 s31, s15, s93
	s_cselect_b32 s30, s23, s92
	v_lshl_add_u64 v[214:215], s[26:27], 0, v[180:181]
	s_add_i32 m0, s25, 0xc000
	ds_read_b128 v[160:163], v205
	ds_read_b128 v[164:167], v205 offset:1024
	ds_read_b128 v[168:171], v205 offset:2048
	ds_read_b128 v[172:175], v205 offset:3072
	ds_read_b128 v[188:191], v205 offset:4096
	ds_read_b128 v[192:195], v205 offset:5120
	ds_read_b128 v[196:199], v205 offset:6144
	ds_read_b128 v[210:213], v205 offset:7168
	global_load_lds_dwordx4 v[214:215], off
	v_lshl_add_u64 v[214:215], s[26:27], 0, v[182:183]
	s_add_i32 m0, s25, 0xe000
	s_nop 0
	global_load_lds_dwordx4 v[214:215], off
	s_waitcnt vmcnt(8)
	s_waitcnt lgkmcnt(0)
	s_setprio 1
	s_barrier
	v_mfma_f32_16x16x32_bf16 v[124:127], v[128:131], v[160:163], 0
	v_mfma_f32_16x16x32_bf16 v[120:123], v[136:139], v[160:163], 0
	v_mfma_f32_16x16x32_bf16 v[108:111], v[128:131], v[168:171], 0
	v_mfma_f32_16x16x32_bf16 v[104:107], v[136:139], v[168:171], 0
	v_mfma_f32_16x16x32_bf16 v[92:95], v[128:131], v[188:191], 0
	v_mfma_f32_16x16x32_bf16 v[88:91], v[136:139], v[188:191], 0
	v_mfma_f32_16x16x32_bf16 v[76:79], v[128:131], v[196:199], 0
	v_mfma_f32_16x16x32_bf16 v[72:75], v[136:139], v[196:199], 0
	v_mfma_f32_16x16x32_bf16 v[124:127], v[132:135], v[164:167], v[124:127]
	v_mfma_f32_16x16x32_bf16 v[120:123], v[140:143], v[164:167], v[120:123]
	v_mfma_f32_16x16x32_bf16 v[108:111], v[132:135], v[172:175], v[108:111]
	v_mfma_f32_16x16x32_bf16 v[104:107], v[140:143], v[172:175], v[104:107]
	v_mfma_f32_16x16x32_bf16 v[92:95], v[132:135], v[192:195], v[92:95]
	v_mfma_f32_16x16x32_bf16 v[88:91], v[140:143], v[192:195], v[88:91]
	v_mfma_f32_16x16x32_bf16 v[76:79], v[132:135], v[210:213], v[76:79]
	v_mfma_f32_16x16x32_bf16 v[72:75], v[140:143], v[210:213], v[72:75]
	s_setprio 0
	s_setprio 1
	v_mfma_f32_16x16x32_bf16 v[116:119], v[144:147], v[160:163], 0
	v_mfma_f32_16x16x32_bf16 v[112:115], v[152:155], v[160:163], 0
	v_mfma_f32_16x16x32_bf16 v[100:103], v[144:147], v[168:171], 0
	v_mfma_f32_16x16x32_bf16 v[96:99], v[152:155], v[168:171], 0
	v_mfma_f32_16x16x32_bf16 v[84:87], v[144:147], v[188:191], 0
	v_mfma_f32_16x16x32_bf16 v[80:83], v[152:155], v[188:191], 0
	v_mfma_f32_16x16x32_bf16 v[68:71], v[144:147], v[196:199], 0
	v_mfma_f32_16x16x32_bf16 v[64:67], v[152:155], v[196:199], 0
	v_mfma_f32_16x16x32_bf16 v[116:119], v[148:151], v[164:167], v[116:119]
	v_mfma_f32_16x16x32_bf16 v[112:115], v[156:159], v[164:167], v[112:115]
	v_mfma_f32_16x16x32_bf16 v[100:103], v[148:151], v[172:175], v[100:103]
	v_mfma_f32_16x16x32_bf16 v[96:99], v[156:159], v[172:175], v[96:99]
	v_mfma_f32_16x16x32_bf16 v[84:87], v[148:151], v[192:195], v[84:87]
	v_mfma_f32_16x16x32_bf16 v[80:83], v[156:159], v[192:195], v[80:83]
	v_mfma_f32_16x16x32_bf16 v[68:71], v[148:151], v[210:213], v[68:71]
	v_mfma_f32_16x16x32_bf16 v[64:67], v[156:159], v[210:213], v[64:67]
	s_barrier
	s_setprio 0
	s_add_i32 s26, s90, s51
	v_lshl_add_u64 v[214:215], s[30:31], 0, v[176:177]
	s_mov_b32 m0, s26
	ds_read_b128 v[160:163], v205 offset:16384
	ds_read_b128 v[164:167], v205 offset:17408
	ds_read_b128 v[168:171], v205 offset:18432
	ds_read_b128 v[172:175], v205 offset:19456
	ds_read_b128 v[188:191], v205 offset:20480
	ds_read_b128 v[192:195], v205 offset:21504
	ds_read_b128 v[196:199], v205 offset:22528
	ds_read_b128 v[210:213], v205 offset:23552
	global_load_lds_dwordx4 v[214:215], off
	s_add_i32 m0, s26, 0x2000
	s_add_u32 s26, s30, 0x40000
	v_lshl_add_u64 v[216:217], s[30:31], 0, v[178:179]
	s_addc_u32 s27, s31, 0
	s_add_i32 s95, s91, s51
	global_load_lds_dwordx4 v[216:217], off
	v_lshl_add_u64 v[218:219], s[26:27], 0, v[176:177]
	s_mov_b32 m0, s95
	v_lshl_add_u64 v[220:221], s[34:35], 0, v[178:179]
	global_load_lds_dwordx4 v[218:219], off
	v_lshl_add_u64 v[218:219], s[26:27], 0, v[178:179]
	s_add_i32 m0, s95, 0x2000
	s_nop 0
	global_load_lds_dwordx4 v[218:219], off
	v_lshl_add_u64 v[218:219], s[34:35], 0, v[176:177]
	s_mov_b32 m0, s25
	s_nop 0
	global_load_lds_dwordx4 v[218:219], off
	s_mov_b32 m0, s76
	s_nop 0
	global_load_lds_dwordx4 v[220:221], off
	s_waitcnt vmcnt(8)
	s_waitcnt lgkmcnt(0)
	s_setprio 1
	s_barrier
	v_mfma_f32_16x16x32_bf16 v[60:63], v[128:131], v[160:163], 0
	v_mfma_f32_16x16x32_bf16 v[56:59], v[136:139], v[160:163], 0
	v_mfma_f32_16x16x32_bf16 v[44:47], v[128:131], v[168:171], 0
	v_mfma_f32_16x16x32_bf16 v[40:43], v[136:139], v[168:171], 0
	v_mfma_f32_16x16x32_bf16 v[28:31], v[128:131], v[188:191], 0
	v_mfma_f32_16x16x32_bf16 v[24:27], v[136:139], v[188:191], 0
	v_mfma_f32_16x16x32_bf16 v[12:15], v[128:131], v[196:199], 0
	v_mfma_f32_16x16x32_bf16 v[8:11], v[136:139], v[196:199], 0
	v_mfma_f32_16x16x32_bf16 v[60:63], v[132:135], v[164:167], v[60:63]
	v_mfma_f32_16x16x32_bf16 v[56:59], v[140:143], v[164:167], v[56:59]
	v_mfma_f32_16x16x32_bf16 v[44:47], v[132:135], v[172:175], v[44:47]
	v_mfma_f32_16x16x32_bf16 v[40:43], v[140:143], v[172:175], v[40:43]
	v_mfma_f32_16x16x32_bf16 v[28:31], v[132:135], v[192:195], v[28:31]
	v_mfma_f32_16x16x32_bf16 v[24:27], v[140:143], v[192:195], v[24:27]
	v_mfma_f32_16x16x32_bf16 v[12:15], v[132:135], v[210:213], v[12:15]
	v_mfma_f32_16x16x32_bf16 v[8:11], v[140:143], v[210:213], v[8:11]
	s_setprio 0
	s_setprio 1
	v_mfma_f32_16x16x32_bf16 v[52:55], v[144:147], v[160:163], 0
	v_mfma_f32_16x16x32_bf16 v[48:51], v[152:155], v[160:163], 0
	v_mfma_f32_16x16x32_bf16 v[36:39], v[144:147], v[168:171], 0
	v_mfma_f32_16x16x32_bf16 v[32:35], v[152:155], v[168:171], 0
	v_mfma_f32_16x16x32_bf16 v[20:23], v[144:147], v[188:191], 0
	v_mfma_f32_16x16x32_bf16 v[16:19], v[152:155], v[188:191], 0
	v_mfma_f32_16x16x32_bf16 v[4:7], v[144:147], v[196:199], 0
	v_mfma_f32_16x16x32_bf16 v[0:3], v[152:155], v[196:199], 0
	v_mfma_f32_16x16x32_bf16 v[52:55], v[148:151], v[164:167], v[52:55]
	v_mfma_f32_16x16x32_bf16 v[48:51], v[156:159], v[164:167], v[48:51]
	v_mfma_f32_16x16x32_bf16 v[36:39], v[148:151], v[172:175], v[36:39]
	v_mfma_f32_16x16x32_bf16 v[32:35], v[156:159], v[172:175], v[32:35]
	v_mfma_f32_16x16x32_bf16 v[20:23], v[148:151], v[192:195], v[20:23]
	v_mfma_f32_16x16x32_bf16 v[16:19], v[156:159], v[192:195], v[16:19]
	v_mfma_f32_16x16x32_bf16 v[4:7], v[148:151], v[210:213], v[4:7]
	v_mfma_f32_16x16x32_bf16 v[0:3], v[156:159], v[210:213], v[0:3]
	s_barrier
	s_setprio 0
	s_add_i32 s95, 0, 0x18000
	s_add_i32 s96, 0, 0x1c000
	v_add_u32_e32 v140, s95, v201
	v_add_u32_e32 v156, s96, v201
	ds_read_b128 v[128:131], v140
	ds_read_b128 v[132:135], v140 offset:1024
	ds_read_b128 v[136:139], v140 offset:2048
	ds_read_b128 v[140:143], v140 offset:3072
	ds_read_b128 v[144:147], v156
	ds_read_b128 v[148:151], v156 offset:1024
	ds_read_b128 v[152:155], v156 offset:2048
	ds_read_b128 v[156:159], v156 offset:3072
	s_add_u32 s26, s34, 0x40000
	s_addc_u32 s27, s35, 0
	s_mov_b32 m0, s77
	v_lshl_add_u64 v[222:223], s[26:27], 0, v[176:177]
	ds_read_b128 v[160:163], v205 offset:32768
	ds_read_b128 v[164:167], v205 offset:33792
	ds_read_b128 v[168:171], v205 offset:34816
	ds_read_b128 v[172:175], v205 offset:35840
	ds_read_b128 v[188:191], v205 offset:36864
	ds_read_b128 v[192:195], v205 offset:37888
	ds_read_b128 v[196:199], v205 offset:38912
	ds_read_b128 v[210:213], v205 offset:39936
	global_load_lds_dwordx4 v[222:223], off
	v_lshl_add_u64 v[222:223], s[26:27], 0, v[178:179]
	s_mov_b32 m0, s78
	s_nop 0
	global_load_lds_dwordx4 v[222:223], off
	s_waitcnt vmcnt(8)
	s_waitcnt lgkmcnt(0)
	s_setprio 1
	s_barrier
	v_mfma_f32_16x16x32_bf16 v[124:127], v[128:131], v[160:163], v[124:127]
	v_mfma_f32_16x16x32_bf16 v[120:123], v[136:139], v[160:163], v[120:123]
	v_mfma_f32_16x16x32_bf16 v[108:111], v[128:131], v[168:171], v[108:111]
	v_mfma_f32_16x16x32_bf16 v[104:107], v[136:139], v[168:171], v[104:107]
	v_mfma_f32_16x16x32_bf16 v[92:95], v[128:131], v[188:191], v[92:95]
	v_mfma_f32_16x16x32_bf16 v[88:91], v[136:139], v[188:191], v[88:91]
	v_mfma_f32_16x16x32_bf16 v[76:79], v[128:131], v[196:199], v[76:79]
	v_mfma_f32_16x16x32_bf16 v[72:75], v[136:139], v[196:199], v[72:75]
	v_mfma_f32_16x16x32_bf16 v[124:127], v[132:135], v[164:167], v[124:127]
	v_mfma_f32_16x16x32_bf16 v[120:123], v[140:143], v[164:167], v[120:123]
	v_mfma_f32_16x16x32_bf16 v[108:111], v[132:135], v[172:175], v[108:111]
	v_mfma_f32_16x16x32_bf16 v[104:107], v[140:143], v[172:175], v[104:107]
	v_mfma_f32_16x16x32_bf16 v[92:95], v[132:135], v[192:195], v[92:95]
	v_mfma_f32_16x16x32_bf16 v[88:91], v[140:143], v[192:195], v[88:91]
	v_mfma_f32_16x16x32_bf16 v[76:79], v[132:135], v[210:213], v[76:79]
	v_mfma_f32_16x16x32_bf16 v[72:75], v[140:143], v[210:213], v[72:75]
	s_setprio 0
	s_setprio 1
	v_mfma_f32_16x16x32_bf16 v[116:119], v[144:147], v[160:163], v[116:119]
	v_mfma_f32_16x16x32_bf16 v[112:115], v[152:155], v[160:163], v[112:115]
	v_mfma_f32_16x16x32_bf16 v[100:103], v[144:147], v[168:171], v[100:103]
	v_mfma_f32_16x16x32_bf16 v[96:99], v[152:155], v[168:171], v[96:99]
	v_mfma_f32_16x16x32_bf16 v[84:87], v[144:147], v[188:191], v[84:87]
	v_mfma_f32_16x16x32_bf16 v[80:83], v[152:155], v[188:191], v[80:83]
	v_mfma_f32_16x16x32_bf16 v[68:71], v[144:147], v[196:199], v[68:71]
	v_mfma_f32_16x16x32_bf16 v[64:67], v[152:155], v[196:199], v[64:67]
	v_mfma_f32_16x16x32_bf16 v[116:119], v[148:151], v[164:167], v[116:119]
	v_mfma_f32_16x16x32_bf16 v[112:115], v[156:159], v[164:167], v[112:115]
	v_mfma_f32_16x16x32_bf16 v[100:103], v[148:151], v[172:175], v[100:103]
	v_mfma_f32_16x16x32_bf16 v[96:99], v[156:159], v[172:175], v[96:99]
	v_mfma_f32_16x16x32_bf16 v[84:87], v[148:151], v[192:195], v[84:87]
	v_mfma_f32_16x16x32_bf16 v[80:83], v[156:159], v[192:195], v[80:83]
	v_mfma_f32_16x16x32_bf16 v[68:71], v[148:151], v[210:213], v[68:71]
	v_mfma_f32_16x16x32_bf16 v[64:67], v[156:159], v[210:213], v[64:67]
	s_barrier
	s_setprio 0
	s_add_i32 s26, s95, s51
	v_lshl_add_u64 v[214:215], v[214:215], 0, s[10:11]
	s_mov_b32 m0, s26
	ds_read_b128 v[160:163], v205 offset:49152
	ds_read_b128 v[164:167], v205 offset:50176
	ds_read_b128 v[168:171], v205 offset:51200
	ds_read_b128 v[172:175], v205 offset:52224
	ds_read_b128 v[188:191], v205 offset:53248
	ds_read_b128 v[192:195], v205 offset:54272
	ds_read_b128 v[196:199], v205 offset:55296
	ds_read_b128 v[210:213], v205 offset:56320
	global_load_lds_dwordx4 v[214:215], off
	s_add_i32 m0, s26, 0x2000
	s_add_u32 s26, s30, 0x40080
	v_lshl_add_u64 v[214:215], v[216:217], 0, s[10:11]
	s_addc_u32 s27, s31, 0
	s_add_i32 s30, s96, s51
	global_load_lds_dwordx4 v[214:215], off
	v_lshl_add_u64 v[214:215], s[26:27], 0, v[176:177]
	s_mov_b32 m0, s30
	s_nop 0
	global_load_lds_dwordx4 v[214:215], off
	v_lshl_add_u64 v[214:215], s[26:27], 0, v[178:179]
	s_add_i32 m0, s30, 0x2000
	s_nop 0
	global_load_lds_dwordx4 v[214:215], off
	v_lshl_add_u64 v[214:215], v[218:219], 0, s[10:11]
	s_mov_b32 m0, s86
	s_nop 0
	global_load_lds_dwordx4 v[214:215], off
	v_lshl_add_u64 v[214:215], v[220:221], 0, s[10:11]
	s_mov_b32 m0, s87
	s_nop 0
	global_load_lds_dwordx4 v[214:215], off
	s_waitcnt vmcnt(8)
	s_waitcnt lgkmcnt(0)
	s_setprio 1
	s_barrier
	v_mfma_f32_16x16x32_bf16 v[60:63], v[128:131], v[160:163], v[60:63]
	v_mfma_f32_16x16x32_bf16 v[56:59], v[136:139], v[160:163], v[56:59]
	v_mfma_f32_16x16x32_bf16 v[44:47], v[128:131], v[168:171], v[44:47]
	v_mfma_f32_16x16x32_bf16 v[40:43], v[136:139], v[168:171], v[40:43]
	v_mfma_f32_16x16x32_bf16 v[28:31], v[128:131], v[188:191], v[28:31]
	v_mfma_f32_16x16x32_bf16 v[24:27], v[136:139], v[188:191], v[24:27]
	v_mfma_f32_16x16x32_bf16 v[12:15], v[128:131], v[196:199], v[12:15]
	v_mfma_f32_16x16x32_bf16 v[8:11], v[136:139], v[196:199], v[8:11]
	v_mfma_f32_16x16x32_bf16 v[60:63], v[132:135], v[164:167], v[60:63]
	v_mfma_f32_16x16x32_bf16 v[56:59], v[140:143], v[164:167], v[56:59]
	v_mfma_f32_16x16x32_bf16 v[44:47], v[132:135], v[172:175], v[44:47]
	v_mfma_f32_16x16x32_bf16 v[40:43], v[140:143], v[172:175], v[40:43]
	v_mfma_f32_16x16x32_bf16 v[28:31], v[132:135], v[192:195], v[28:31]
	v_mfma_f32_16x16x32_bf16 v[24:27], v[140:143], v[192:195], v[24:27]
	v_mfma_f32_16x16x32_bf16 v[12:15], v[132:135], v[210:213], v[12:15]
	v_mfma_f32_16x16x32_bf16 v[8:11], v[140:143], v[210:213], v[8:11]
	s_setprio 0
	s_setprio 1
	v_mfma_f32_16x16x32_bf16 v[52:55], v[144:147], v[160:163], v[52:55]
	v_mfma_f32_16x16x32_bf16 v[48:51], v[152:155], v[160:163], v[48:51]
	v_mfma_f32_16x16x32_bf16 v[36:39], v[144:147], v[168:171], v[36:39]
	v_mfma_f32_16x16x32_bf16 v[32:35], v[152:155], v[168:171], v[32:35]
	v_mfma_f32_16x16x32_bf16 v[20:23], v[144:147], v[188:191], v[20:23]
	v_mfma_f32_16x16x32_bf16 v[16:19], v[152:155], v[188:191], v[16:19]
	v_mfma_f32_16x16x32_bf16 v[4:7], v[144:147], v[196:199], v[4:7]
	v_mfma_f32_16x16x32_bf16 v[0:3], v[152:155], v[196:199], v[0:3]
	v_mfma_f32_16x16x32_bf16 v[52:55], v[148:151], v[164:167], v[52:55]
	v_mfma_f32_16x16x32_bf16 v[48:51], v[156:159], v[164:167], v[48:51]
	v_mfma_f32_16x16x32_bf16 v[36:39], v[148:151], v[172:175], v[36:39]
	v_mfma_f32_16x16x32_bf16 v[32:35], v[156:159], v[172:175], v[32:35]
	v_mfma_f32_16x16x32_bf16 v[20:23], v[148:151], v[192:195], v[20:23]
	v_mfma_f32_16x16x32_bf16 v[16:19], v[156:159], v[192:195], v[16:19]
	v_mfma_f32_16x16x32_bf16 v[4:7], v[148:151], v[210:213], v[4:7]
	v_mfma_f32_16x16x32_bf16 v[0:3], v[156:159], v[210:213], v[0:3]
	s_barrier
	s_setprio 0
	s_add_i32 s94, s94, 2
	s_add_u32 s92, s92, 0x100
	s_addc_u32 s93, s93, 0
	s_cmp_gt_u32 s94, 13
	s_mov_b64 s[26:27], s[28:29]

.LBB0_693:
	s_ashr_i32 s17, s16, 31
	s_lshl_b64 s[18:19], s[16:17], 19
	s_add_u32 s18, s82, s18
	s_addc_u32 s19, s83, s19
	s_and_b64 s[20:21], s[0:1], exec
	s_cselect_b32 s17, s19, s25
	s_cselect_b32 s87, s18, s24
	s_ashr_i32 s15, s14, 31
	s_lshl_b64 s[20:21], s[14:15], 19
	s_add_u32 s20, s35, s20
	s_addc_u32 s21, s36, s21
	s_and_b64 s[28:29], s[0:1], exec
	s_cselect_b32 s15, s21, s27
	s_cselect_b32 s88, s20, s26
	s_add_u32 s24, s24, 0x40080
	s_addc_u32 s25, s25, 0
	s_add_u32 s89, s26, 0x100
	s_addc_u32 s90, s27, 0
	s_mov_b32 s91, -2
	s_nop 0
	s_nop 0
	s_nop 0
	s_nop 0
	s_nop 0
	s_nop 0
	s_nop 0
	s_nop 0
	s_nop 0
	s_nop 0
	s_nop 0
	s_nop 0
	s_nop 0
	s_nop 0
	s_nop 0
	ds_read_b128 v[144:147], v155
	ds_read_b128 v[148:151], v155 offset:1024
	ds_read_b128 v[160:163], v155 offset:2048
	ds_read_b128 v[164:167], v155 offset:3072
	ds_read_b128 v[168:171], v156
	ds_read_b128 v[172:175], v156 offset:1024
	ds_read_b128 v[176:179], v156 offset:2048
	ds_read_b128 v[180:183], v156 offset:3072
	s_add_u32 s26, s24, 0xfffc0080
	s_addc_u32 s27, s25, -1
	s_cmp_eq_u32 s91, 12
	s_cselect_b32 s29, s17, s27
	s_cselect_b32 s28, s87, s26
	s_cselect_b32 s27, s15, s90
	s_cselect_b32 s26, s88, s89
	v_lshl_add_u64 v[204:205], s[24:25], 0, v[136:137]
	s_add_i32 m0, s23, 0xc000
	ds_read_b128 v[184:187], v157
	ds_read_b128 v[188:191], v157 offset:1024
	ds_read_b128 v[192:195], v157 offset:2048
	ds_read_b128 v[196:199], v157 offset:3072
	ds_read_b128 v[200:203], v157 offset:4096
	ds_read_b128 v[208:211], v157 offset:5120
	ds_read_b128 v[212:215], v157 offset:6144
	ds_read_b128 v[216:219], v157 offset:7168
	global_load_lds_dwordx4 v[204:205], off
	v_lshl_add_u64 v[204:205], s[24:25], 0, v[138:139]
	s_add_i32 m0, s23, 0xe000
	s_nop 0
	global_load_lds_dwordx4 v[204:205], off
	s_waitcnt vmcnt(8)
	s_waitcnt lgkmcnt(0)
	s_setprio 1
	s_barrier
	v_mfma_f32_16x16x32_bf16 v[124:127], v[144:147], v[184:187], 0
	v_mfma_f32_16x16x32_bf16 v[120:123], v[160:163], v[184:187], 0
	v_mfma_f32_16x16x32_bf16 v[116:119], v[144:147], v[192:195], 0
	v_mfma_f32_16x16x32_bf16 v[104:107], v[160:163], v[192:195], 0
	v_mfma_f32_16x16x32_bf16 v[92:95], v[144:147], v[200:203], 0
	v_mfma_f32_16x16x32_bf16 v[88:91], v[160:163], v[200:203], 0
	v_mfma_f32_16x16x32_bf16 v[76:79], v[144:147], v[212:215], 0
	v_mfma_f32_16x16x32_bf16 v[72:75], v[160:163], v[212:215], 0
	v_mfma_f32_16x16x32_bf16 v[124:127], v[148:151], v[188:191], v[124:127]
	v_mfma_f32_16x16x32_bf16 v[120:123], v[164:167], v[188:191], v[120:123]
	v_mfma_f32_16x16x32_bf16 v[116:119], v[148:151], v[196:199], v[116:119]
	v_mfma_f32_16x16x32_bf16 v[104:107], v[164:167], v[196:199], v[104:107]
	v_mfma_f32_16x16x32_bf16 v[92:95], v[148:151], v[208:211], v[92:95]
	v_mfma_f32_16x16x32_bf16 v[88:91], v[164:167], v[208:211], v[88:91]
	v_mfma_f32_16x16x32_bf16 v[76:79], v[148:151], v[216:219], v[76:79]
	v_mfma_f32_16x16x32_bf16 v[72:75], v[164:167], v[216:219], v[72:75]
	s_setprio 0
	s_setprio 1
	v_mfma_f32_16x16x32_bf16 v[112:115], v[168:171], v[184:187], 0
	v_mfma_f32_16x16x32_bf16 v[108:111], v[176:179], v[184:187], 0
	v_mfma_f32_16x16x32_bf16 v[100:103], v[168:171], v[192:195], 0
	v_mfma_f32_16x16x32_bf16 v[96:99], v[176:179], v[192:195], 0
	v_mfma_f32_16x16x32_bf16 v[84:87], v[168:171], v[200:203], 0
	v_mfma_f32_16x16x32_bf16 v[80:83], v[176:179], v[200:203], 0
	v_mfma_f32_16x16x32_bf16 v[68:71], v[168:171], v[212:215], 0
	v_mfma_f32_16x16x32_bf16 v[64:67], v[176:179], v[212:215], 0
	v_mfma_f32_16x16x32_bf16 v[112:115], v[172:175], v[188:191], v[112:115]
	v_mfma_f32_16x16x32_bf16 v[108:111], v[180:183], v[188:191], v[108:111]
	v_mfma_f32_16x16x32_bf16 v[100:103], v[172:175], v[196:199], v[100:103]
	v_mfma_f32_16x16x32_bf16 v[96:99], v[180:183], v[196:199], v[96:99]
	v_mfma_f32_16x16x32_bf16 v[84:87], v[172:175], v[208:211], v[84:87]
	v_mfma_f32_16x16x32_bf16 v[80:83], v[180:183], v[208:211], v[80:83]
	v_mfma_f32_16x16x32_bf16 v[68:71], v[172:175], v[216:219], v[68:71]
	v_mfma_f32_16x16x32_bf16 v[64:67], v[180:183], v[216:219], v[64:67]
	s_barrier
	s_setprio 0
	s_add_i32 s92, s78, s37
	v_lshl_add_u64 v[204:205], s[26:27], 0, v[130:131]
	s_mov_b32 m0, s92
	ds_read_b128 v[184:187], v157 offset:16384
	ds_read_b128 v[188:191], v157 offset:17408
	ds_read_b128 v[192:195], v157 offset:18432
	ds_read_b128 v[196:199], v157 offset:19456
	ds_read_b128 v[200:203], v157 offset:20480
	ds_read_b128 v[208:211], v157 offset:21504
	ds_read_b128 v[212:215], v157 offset:22528
	ds_read_b128 v[216:219], v157 offset:23552
	global_load_lds_dwordx4 v[204:205], off
	s_add_i32 m0, s92, 0x2000
	s_add_u32 s92, s26, 0x40000
	v_lshl_add_u64 v[220:221], s[26:27], 0, v[134:135]
	s_addc_u32 s93, s27, 0
	s_add_i32 s94, s79, s37
	global_load_lds_dwordx4 v[220:221], off
	v_lshl_add_u64 v[222:223], s[92:93], 0, v[130:131]
	s_mov_b32 m0, s94
	v_lshl_add_u64 v[224:225], s[28:29], 0, v[132:133]
	global_load_lds_dwordx4 v[222:223], off
	v_lshl_add_u64 v[222:223], s[92:93], 0, v[134:135]
	s_add_i32 m0, s94, 0x2000
	s_nop 0
	global_load_lds_dwordx4 v[222:223], off
	v_lshl_add_u64 v[222:223], s[28:29], 0, v[128:129]
	s_mov_b32 m0, s23
	s_nop 0
	global_load_lds_dwordx4 v[222:223], off
	s_mov_b32 m0, s39
	s_nop 0
	global_load_lds_dwordx4 v[224:225], off
	s_waitcnt vmcnt(8)
	s_waitcnt lgkmcnt(0)
	s_setprio 1
	s_barrier
	v_mfma_f32_16x16x32_bf16 v[60:63], v[144:147], v[184:187], 0
	v_mfma_f32_16x16x32_bf16 v[56:59], v[160:163], v[184:187], 0
	v_mfma_f32_16x16x32_bf16 v[44:47], v[144:147], v[192:195], 0
	v_mfma_f32_16x16x32_bf16 v[40:43], v[160:163], v[192:195], 0
	v_mfma_f32_16x16x32_bf16 v[28:31], v[144:147], v[200:203], 0
	v_mfma_f32_16x16x32_bf16 v[24:27], v[160:163], v[200:203], 0
	v_mfma_f32_16x16x32_bf16 v[12:15], v[144:147], v[212:215], 0
	v_mfma_f32_16x16x32_bf16 v[8:11], v[160:163], v[212:215], 0
	v_mfma_f32_16x16x32_bf16 v[60:63], v[148:151], v[188:191], v[60:63]
	v_mfma_f32_16x16x32_bf16 v[56:59], v[164:167], v[188:191], v[56:59]
	v_mfma_f32_16x16x32_bf16 v[44:47], v[148:151], v[196:199], v[44:47]
	v_mfma_f32_16x16x32_bf16 v[40:43], v[164:167], v[196:199], v[40:43]
	v_mfma_f32_16x16x32_bf16 v[28:31], v[148:151], v[208:211], v[28:31]
	v_mfma_f32_16x16x32_bf16 v[24:27], v[164:167], v[208:211], v[24:27]
	v_mfma_f32_16x16x32_bf16 v[12:15], v[148:151], v[216:219], v[12:15]
	v_mfma_f32_16x16x32_bf16 v[8:11], v[164:167], v[216:219], v[8:11]
	s_setprio 0
	s_setprio 1
	v_mfma_f32_16x16x32_bf16 v[52:55], v[168:171], v[184:187], 0
	v_mfma_f32_16x16x32_bf16 v[48:51], v[176:179], v[184:187], 0
	v_mfma_f32_16x16x32_bf16 v[36:39], v[168:171], v[192:195], 0
	v_mfma_f32_16x16x32_bf16 v[32:35], v[176:179], v[192:195], 0
	v_mfma_f32_16x16x32_bf16 v[20:23], v[168:171], v[200:203], 0
	v_mfma_f32_16x16x32_bf16 v[16:19], v[176:179], v[200:203], 0
	v_mfma_f32_16x16x32_bf16 v[4:7], v[168:171], v[212:215], 0
	v_mfma_f32_16x16x32_bf16 v[0:3], v[176:179], v[212:215], 0
	v_mfma_f32_16x16x32_bf16 v[52:55], v[172:175], v[188:191], v[52:55]
	v_mfma_f32_16x16x32_bf16 v[48:51], v[180:183], v[188:191], v[48:51]
	v_mfma_f32_16x16x32_bf16 v[36:39], v[172:175], v[196:199], v[36:39]
	v_mfma_f32_16x16x32_bf16 v[32:35], v[180:183], v[196:199], v[32:35]
	v_mfma_f32_16x16x32_bf16 v[20:23], v[172:175], v[208:211], v[20:23]
	v_mfma_f32_16x16x32_bf16 v[16:19], v[180:183], v[208:211], v[16:19]
	v_mfma_f32_16x16x32_bf16 v[4:7], v[172:175], v[216:219], v[4:7]
	v_mfma_f32_16x16x32_bf16 v[0:3], v[180:183], v[216:219], v[0:3]
	s_barrier
	s_setprio 0
	s_add_i32 s92, 0, 0x18000
	v_add_u32_e32 v159, s92, v153
	s_add_i32 s93, 0, 0x1c000
	ds_read_b128 v[144:147], v159
	ds_read_b128 v[148:151], v159 offset:1024
	ds_read_b128 v[160:163], v159 offset:2048
	ds_read_b128 v[164:167], v159 offset:3072
	v_add_u32_e32 v159, s93, v153
	ds_read_b128 v[168:171], v159
	ds_read_b128 v[172:175], v159 offset:1024
	ds_read_b128 v[176:179], v159 offset:2048
	ds_read_b128 v[180:183], v159 offset:3072
	s_add_u32 s28, s28, 0x40000
	s_addc_u32 s29, s29, 0
	s_mov_b32 m0, s40
	v_lshl_add_u64 v[226:227], s[28:29], 0, v[128:129]
	ds_read_b128 v[184:187], v157 offset:32768
	ds_read_b128 v[188:191], v157 offset:33792
	ds_read_b128 v[192:195], v157 offset:34816
	ds_read_b128 v[196:199], v157 offset:35840
	ds_read_b128 v[200:203], v157 offset:36864
	ds_read_b128 v[208:211], v157 offset:37888
	ds_read_b128 v[212:215], v157 offset:38912
	ds_read_b128 v[216:219], v157 offset:39936
	global_load_lds_dwordx4 v[226:227], off
	v_lshl_add_u64 v[226:227], s[28:29], 0, v[132:133]
	s_mov_b32 m0, s41
	s_nop 0
	global_load_lds_dwordx4 v[226:227], off
	s_waitcnt vmcnt(8)
	s_waitcnt lgkmcnt(0)
	s_setprio 1
	s_barrier
	v_mfma_f32_16x16x32_bf16 v[124:127], v[144:147], v[184:187], v[124:127]
	v_mfma_f32_16x16x32_bf16 v[120:123], v[160:163], v[184:187], v[120:123]
	v_mfma_f32_16x16x32_bf16 v[116:119], v[144:147], v[192:195], v[116:119]
	v_mfma_f32_16x16x32_bf16 v[104:107], v[160:163], v[192:195], v[104:107]
	v_mfma_f32_16x16x32_bf16 v[92:95], v[144:147], v[200:203], v[92:95]
	v_mfma_f32_16x16x32_bf16 v[88:91], v[160:163], v[200:203], v[88:91]
	v_mfma_f32_16x16x32_bf16 v[76:79], v[144:147], v[212:215], v[76:79]
	v_mfma_f32_16x16x32_bf16 v[72:75], v[160:163], v[212:215], v[72:75]
	v_mfma_f32_16x16x32_bf16 v[124:127], v[148:151], v[188:191], v[124:127]
	v_mfma_f32_16x16x32_bf16 v[120:123], v[164:167], v[188:191], v[120:123]
	v_mfma_f32_16x16x32_bf16 v[116:119], v[148:151], v[196:199], v[116:119]
	v_mfma_f32_16x16x32_bf16 v[104:107], v[164:167], v[196:199], v[104:107]
	v_mfma_f32_16x16x32_bf16 v[92:95], v[148:151], v[208:211], v[92:95]
	v_mfma_f32_16x16x32_bf16 v[88:91], v[164:167], v[208:211], v[88:91]
	v_mfma_f32_16x16x32_bf16 v[76:79], v[148:151], v[216:219], v[76:79]
	v_mfma_f32_16x16x32_bf16 v[72:75], v[164:167], v[216:219], v[72:75]
	s_setprio 0
	s_setprio 1
	v_mfma_f32_16x16x32_bf16 v[112:115], v[168:171], v[184:187], v[112:115]
	v_mfma_f32_16x16x32_bf16 v[108:111], v[176:179], v[184:187], v[108:111]
	v_mfma_f32_16x16x32_bf16 v[100:103], v[168:171], v[192:195], v[100:103]
	v_mfma_f32_16x16x32_bf16 v[96:99], v[176:179], v[192:195], v[96:99]
	v_mfma_f32_16x16x32_bf16 v[84:87], v[168:171], v[200:203], v[84:87]
	v_mfma_f32_16x16x32_bf16 v[80:83], v[176:179], v[200:203], v[80:83]
	v_mfma_f32_16x16x32_bf16 v[68:71], v[168:171], v[212:215], v[68:71]
	v_mfma_f32_16x16x32_bf16 v[64:67], v[176:179], v[212:215], v[64:67]
	v_mfma_f32_16x16x32_bf16 v[112:115], v[172:175], v[188:191], v[112:115]
	v_mfma_f32_16x16x32_bf16 v[108:111], v[180:183], v[188:191], v[108:111]
	v_mfma_f32_16x16x32_bf16 v[100:103], v[172:175], v[196:199], v[100:103]
	v_mfma_f32_16x16x32_bf16 v[96:99], v[180:183], v[196:199], v[96:99]
	v_mfma_f32_16x16x32_bf16 v[84:87], v[172:175], v[208:211], v[84:87]
	v_mfma_f32_16x16x32_bf16 v[80:83], v[180:183], v[208:211], v[80:83]
	v_mfma_f32_16x16x32_bf16 v[68:71], v[172:175], v[216:219], v[68:71]
	v_mfma_f32_16x16x32_bf16 v[64:67], v[180:183], v[216:219], v[64:67]
	s_barrier
	s_setprio 0
	s_add_i32 s28, s92, s37
	v_lshl_add_u64 v[204:205], v[204:205], 0, s[8:9]
	s_mov_b32 m0, s28
	ds_read_b128 v[184:187], v157 offset:49152
	ds_read_b128 v[188:191], v157 offset:50176
	ds_read_b128 v[192:195], v157 offset:51200
	ds_read_b128 v[196:199], v157 offset:52224
	ds_read_b128 v[200:203], v157 offset:53248
	ds_read_b128 v[208:211], v157 offset:54272
	ds_read_b128 v[212:215], v157 offset:55296
	ds_read_b128 v[216:219], v157 offset:56320
	global_load_lds_dwordx4 v[204:205], off
	s_add_i32 m0, s28, 0x2000
	s_add_u32 s26, s26, 0x40080
	v_lshl_add_u64 v[204:205], v[220:221], 0, s[8:9]
	s_addc_u32 s27, s27, 0
	s_add_i32 s28, s93, s37
	global_load_lds_dwordx4 v[204:205], off
	v_lshl_add_u64 v[204:205], s[26:27], 0, v[130:131]
	s_mov_b32 m0, s28
	s_nop 0
	global_load_lds_dwordx4 v[204:205], off
	v_lshl_add_u64 v[204:205], s[26:27], 0, v[134:135]
	s_add_i32 m0, s28, 0x2000
	s_nop 0
	global_load_lds_dwordx4 v[204:205], off
	v_lshl_add_u64 v[204:205], v[222:223], 0, s[8:9]
	s_mov_b32 m0, s51
	s_nop 0
	global_load_lds_dwordx4 v[204:205], off
	v_lshl_add_u64 v[204:205], v[224:225], 0, s[8:9]
	s_mov_b32 m0, s76
	s_nop 0
	global_load_lds_dwordx4 v[204:205], off
	s_waitcnt vmcnt(8)
	s_waitcnt lgkmcnt(0)
	s_setprio 1
	s_barrier
	v_mfma_f32_16x16x32_bf16 v[60:63], v[144:147], v[184:187], v[60:63]
	v_mfma_f32_16x16x32_bf16 v[56:59], v[160:163], v[184:187], v[56:59]
	v_mfma_f32_16x16x32_bf16 v[44:47], v[144:147], v[192:195], v[44:47]
	v_mfma_f32_16x16x32_bf16 v[40:43], v[160:163], v[192:195], v[40:43]
	v_mfma_f32_16x16x32_bf16 v[28:31], v[144:147], v[200:203], v[28:31]
	v_mfma_f32_16x16x32_bf16 v[24:27], v[160:163], v[200:203], v[24:27]
	v_mfma_f32_16x16x32_bf16 v[12:15], v[144:147], v[212:215], v[12:15]
	v_mfma_f32_16x16x32_bf16 v[8:11], v[160:163], v[212:215], v[8:11]
	v_mfma_f32_16x16x32_bf16 v[60:63], v[148:151], v[188:191], v[60:63]
	v_mfma_f32_16x16x32_bf16 v[56:59], v[164:167], v[188:191], v[56:59]
	v_mfma_f32_16x16x32_bf16 v[44:47], v[148:151], v[196:199], v[44:47]
	v_mfma_f32_16x16x32_bf16 v[40:43], v[164:167], v[196:199], v[40:43]
	v_mfma_f32_16x16x32_bf16 v[28:31], v[148:151], v[208:211], v[28:31]
	v_mfma_f32_16x16x32_bf16 v[24:27], v[164:167], v[208:211], v[24:27]
	v_mfma_f32_16x16x32_bf16 v[12:15], v[148:151], v[216:219], v[12:15]
	v_mfma_f32_16x16x32_bf16 v[8:11], v[164:167], v[216:219], v[8:11]
	s_setprio 0
	s_setprio 1
	v_mfma_f32_16x16x32_bf16 v[52:55], v[168:171], v[184:187], v[52:55]
	v_mfma_f32_16x16x32_bf16 v[48:51], v[176:179], v[184:187], v[48:51]
	v_mfma_f32_16x16x32_bf16 v[36:39], v[168:171], v[192:195], v[36:39]
	v_mfma_f32_16x16x32_bf16 v[32:35], v[176:179], v[192:195], v[32:35]
	v_mfma_f32_16x16x32_bf16 v[20:23], v[168:171], v[200:203], v[20:23]
	v_mfma_f32_16x16x32_bf16 v[16:19], v[176:179], v[200:203], v[16:19]
	v_mfma_f32_16x16x32_bf16 v[4:7], v[168:171], v[212:215], v[4:7]
	v_mfma_f32_16x16x32_bf16 v[0:3], v[176:179], v[212:215], v[0:3]
	v_mfma_f32_16x16x32_bf16 v[52:55], v[172:175], v[188:191], v[52:55]
	v_mfma_f32_16x16x32_bf16 v[48:51], v[180:183], v[188:191], v[48:51]
	v_mfma_f32_16x16x32_bf16 v[36:39], v[172:175], v[196:199], v[36:39]
	v_mfma_f32_16x16x32_bf16 v[32:35], v[180:183], v[196:199], v[32:35]
	v_mfma_f32_16x16x32_bf16 v[20:23], v[172:175], v[208:211], v[20:23]
	v_mfma_f32_16x16x32_bf16 v[16:19], v[180:183], v[208:211], v[16:19]
	v_mfma_f32_16x16x32_bf16 v[4:7], v[172:175], v[216:219], v[4:7]
	v_mfma_f32_16x16x32_bf16 v[0:3], v[180:183], v[216:219], v[0:3]
	s_barrier
	s_setprio 0
	s_add_i32 s91, s91, 2
	s_add_u32 s24, s24, 0x100
	s_addc_u32 s25, s25, 0
	s_add_u32 s89, s89, 0x100
	s_addc_u32 s90, s90, 0
	s_cmp_gt_u32 s91, 13

.LBB0_851:
	s_ashr_i32 s17, s16, 31
	s_lshl_b64 s[18:19], s[16:17], 21
	s_add_u32 s18, s80, s18
	s_addc_u32 s19, s81, s19
	s_and_b64 s[20:21], s[4:5], exec
	s_cselect_b32 s3, s19, s27
	s_cselect_b32 s17, s18, s26
	s_ashr_i32 s15, s14, 31
	s_lshl_b64 s[20:21], s[14:15], 21
	s_add_u32 s20, s39, s20
	s_addc_u32 s21, s40, s21
	s_and_b64 s[30:31], s[4:5], exec
	s_cselect_b32 s15, s21, s29
	s_cselect_b32 s23, s20, s28
	s_add_u32 s90, s28, 0x100
	s_addc_u32 s91, s29, 0
	s_mov_b32 s92, -2
	s_waitcnt lgkmcnt(0)
	s_nop 0
	ds_read_b128 v[128:131], v211
	ds_read_b128 v[132:135], v211 offset:1024
	ds_read_b128 v[136:139], v211 offset:2048
	ds_read_b128 v[140:143], v211 offset:3072
	ds_read_b128 v[144:147], v212
	ds_read_b128 v[148:151], v212 offset:1024
	ds_read_b128 v[152:155], v212 offset:2048
	ds_read_b128 v[156:159], v212 offset:3072
	s_add_u32 s28, s26, 0x100
	s_addc_u32 s29, s27, 0
	s_cmp_eq_u32 s92, 60
	s_cselect_b32 s35, s3, s29
	s_cselect_b32 s34, s17, s28
	s_cselect_b32 s31, s15, s91
	s_cselect_b32 s30, s23, s90
	v_lshl_add_u64 v[204:205], s[26:27], 0, v[180:181]
	s_add_i32 m0, s25, 0xc000
	ds_read_b128 v[160:163], v213
	ds_read_b128 v[164:167], v213 offset:1024
	ds_read_b128 v[168:171], v213 offset:2048
	ds_read_b128 v[172:175], v213 offset:3072
	ds_read_b128 v[188:191], v213 offset:4096
	ds_read_b128 v[192:195], v213 offset:5120
	ds_read_b128 v[196:199], v213 offset:6144
	ds_read_b128 v[200:203], v213 offset:7168
	global_load_lds_dwordx4 v[204:205], off
	v_lshl_add_u64 v[204:205], s[26:27], 0, v[182:183]
	s_add_i32 m0, s25, 0xe000
	s_nop 0
	global_load_lds_dwordx4 v[204:205], off
	s_waitcnt vmcnt(8)
	s_waitcnt lgkmcnt(0)
	s_setprio 1
	s_barrier
	v_mfma_f32_16x16x32_bf16 v[124:127], v[128:131], v[160:163], 0
	v_mfma_f32_16x16x32_bf16 v[120:123], v[136:139], v[160:163], 0
	v_mfma_f32_16x16x32_bf16 v[108:111], v[128:131], v[168:171], 0
	v_mfma_f32_16x16x32_bf16 v[104:107], v[136:139], v[168:171], 0
	v_mfma_f32_16x16x32_bf16 v[92:95], v[128:131], v[188:191], 0
	v_mfma_f32_16x16x32_bf16 v[88:91], v[136:139], v[188:191], 0
	v_mfma_f32_16x16x32_bf16 v[76:79], v[128:131], v[196:199], 0
	v_mfma_f32_16x16x32_bf16 v[72:75], v[136:139], v[196:199], 0
	v_mfma_f32_16x16x32_bf16 v[124:127], v[132:135], v[164:167], v[124:127]
	v_mfma_f32_16x16x32_bf16 v[120:123], v[140:143], v[164:167], v[120:123]
	v_mfma_f32_16x16x32_bf16 v[108:111], v[132:135], v[172:175], v[108:111]
	v_mfma_f32_16x16x32_bf16 v[104:107], v[140:143], v[172:175], v[104:107]
	v_mfma_f32_16x16x32_bf16 v[92:95], v[132:135], v[192:195], v[92:95]
	v_mfma_f32_16x16x32_bf16 v[88:91], v[140:143], v[192:195], v[88:91]
	v_mfma_f32_16x16x32_bf16 v[76:79], v[132:135], v[200:203], v[76:79]
	v_mfma_f32_16x16x32_bf16 v[72:75], v[140:143], v[200:203], v[72:75]
	s_setprio 0
	s_setprio 1
	v_mfma_f32_16x16x32_bf16 v[116:119], v[144:147], v[160:163], 0
	v_mfma_f32_16x16x32_bf16 v[112:115], v[152:155], v[160:163], 0
	v_mfma_f32_16x16x32_bf16 v[100:103], v[144:147], v[168:171], 0
	v_mfma_f32_16x16x32_bf16 v[96:99], v[152:155], v[168:171], 0
	v_mfma_f32_16x16x32_bf16 v[84:87], v[144:147], v[188:191], 0
	v_mfma_f32_16x16x32_bf16 v[80:83], v[152:155], v[188:191], 0
	v_mfma_f32_16x16x32_bf16 v[68:71], v[144:147], v[196:199], 0
	v_mfma_f32_16x16x32_bf16 v[64:67], v[152:155], v[196:199], 0
	v_mfma_f32_16x16x32_bf16 v[116:119], v[148:151], v[164:167], v[116:119]
	v_mfma_f32_16x16x32_bf16 v[112:115], v[156:159], v[164:167], v[112:115]
	v_mfma_f32_16x16x32_bf16 v[100:103], v[148:151], v[172:175], v[100:103]
	v_mfma_f32_16x16x32_bf16 v[96:99], v[156:159], v[172:175], v[96:99]
	v_mfma_f32_16x16x32_bf16 v[84:87], v[148:151], v[192:195], v[84:87]
	v_mfma_f32_16x16x32_bf16 v[80:83], v[156:159], v[192:195], v[80:83]
	v_mfma_f32_16x16x32_bf16 v[68:71], v[148:151], v[200:203], v[68:71]
	v_mfma_f32_16x16x32_bf16 v[64:67], v[156:159], v[200:203], v[64:67]
	s_barrier
	s_setprio 0
	s_add_i32 s26, s88, s41
	v_lshl_add_u64 v[204:205], s[30:31], 0, v[176:177]
	s_mov_b32 m0, s26
	ds_read_b128 v[160:163], v213 offset:16384
	ds_read_b128 v[164:167], v213 offset:17408
	ds_read_b128 v[168:171], v213 offset:18432
	ds_read_b128 v[172:175], v213 offset:19456
	ds_read_b128 v[188:191], v213 offset:20480
	ds_read_b128 v[192:195], v213 offset:21504
	ds_read_b128 v[196:199], v213 offset:22528
	ds_read_b128 v[200:203], v213 offset:23552
	global_load_lds_dwordx4 v[204:205], off
	s_add_i32 m0, s26, 0x2000
	s_add_u32 s26, s30, 0x100000
	v_lshl_add_u64 v[216:217], s[30:31], 0, v[178:179]
	s_addc_u32 s27, s31, 0
	s_add_i32 s93, s89, s41
	global_load_lds_dwordx4 v[216:217], off
	v_lshl_add_u64 v[218:219], s[26:27], 0, v[176:177]
	s_mov_b32 m0, s93
	v_lshl_add_u64 v[220:221], s[34:35], 0, v[178:179]
	global_load_lds_dwordx4 v[218:219], off
	v_lshl_add_u64 v[218:219], s[26:27], 0, v[178:179]
	s_add_i32 m0, s93, 0x2000
	s_nop 0
	global_load_lds_dwordx4 v[218:219], off
	v_lshl_add_u64 v[218:219], s[34:35], 0, v[176:177]
	s_mov_b32 m0, s25
	s_nop 0
	global_load_lds_dwordx4 v[218:219], off
	s_mov_b32 m0, s50
	s_nop 0
	global_load_lds_dwordx4 v[220:221], off
	s_waitcnt vmcnt(8)
	s_waitcnt lgkmcnt(0)
	s_setprio 1
	s_barrier
	v_mfma_f32_16x16x32_bf16 v[60:63], v[128:131], v[160:163], 0
	v_mfma_f32_16x16x32_bf16 v[56:59], v[136:139], v[160:163], 0
	v_mfma_f32_16x16x32_bf16 v[44:47], v[128:131], v[168:171], 0
	v_mfma_f32_16x16x32_bf16 v[40:43], v[136:139], v[168:171], 0
	v_mfma_f32_16x16x32_bf16 v[28:31], v[128:131], v[188:191], 0
	v_mfma_f32_16x16x32_bf16 v[24:27], v[136:139], v[188:191], 0
	v_mfma_f32_16x16x32_bf16 v[12:15], v[128:131], v[196:199], 0
	v_mfma_f32_16x16x32_bf16 v[8:11], v[136:139], v[196:199], 0
	v_mfma_f32_16x16x32_bf16 v[60:63], v[132:135], v[164:167], v[60:63]
	v_mfma_f32_16x16x32_bf16 v[56:59], v[140:143], v[164:167], v[56:59]
	v_mfma_f32_16x16x32_bf16 v[44:47], v[132:135], v[172:175], v[44:47]
	v_mfma_f32_16x16x32_bf16 v[40:43], v[140:143], v[172:175], v[40:43]
	v_mfma_f32_16x16x32_bf16 v[28:31], v[132:135], v[192:195], v[28:31]
	v_mfma_f32_16x16x32_bf16 v[24:27], v[140:143], v[192:195], v[24:27]
	v_mfma_f32_16x16x32_bf16 v[12:15], v[132:135], v[200:203], v[12:15]
	v_mfma_f32_16x16x32_bf16 v[8:11], v[140:143], v[200:203], v[8:11]
	s_setprio 0
	s_setprio 1
	v_mfma_f32_16x16x32_bf16 v[52:55], v[144:147], v[160:163], 0
	v_mfma_f32_16x16x32_bf16 v[48:51], v[152:155], v[160:163], 0
	v_mfma_f32_16x16x32_bf16 v[36:39], v[144:147], v[168:171], 0
	v_mfma_f32_16x16x32_bf16 v[32:35], v[152:155], v[168:171], 0
	v_mfma_f32_16x16x32_bf16 v[20:23], v[144:147], v[188:191], 0
	v_mfma_f32_16x16x32_bf16 v[16:19], v[152:155], v[188:191], 0
	v_mfma_f32_16x16x32_bf16 v[4:7], v[144:147], v[196:199], 0
	v_mfma_f32_16x16x32_bf16 v[0:3], v[152:155], v[196:199], 0
	v_mfma_f32_16x16x32_bf16 v[52:55], v[148:151], v[164:167], v[52:55]
	v_mfma_f32_16x16x32_bf16 v[48:51], v[156:159], v[164:167], v[48:51]
	v_mfma_f32_16x16x32_bf16 v[36:39], v[148:151], v[172:175], v[36:39]
	v_mfma_f32_16x16x32_bf16 v[32:35], v[156:159], v[172:175], v[32:35]
	v_mfma_f32_16x16x32_bf16 v[20:23], v[148:151], v[192:195], v[20:23]
	v_mfma_f32_16x16x32_bf16 v[16:19], v[156:159], v[192:195], v[16:19]
	v_mfma_f32_16x16x32_bf16 v[4:7], v[148:151], v[200:203], v[4:7]
	v_mfma_f32_16x16x32_bf16 v[0:3], v[156:159], v[200:203], v[0:3]
	s_barrier
	s_setprio 0
	s_add_i32 s93, 0, 0x18000
	s_add_i32 s94, 0, 0x1c000
	v_add_u32_e32 v140, s93, v209
	v_add_u32_e32 v156, s94, v209
	ds_read_b128 v[128:131], v140
	ds_read_b128 v[132:135], v140 offset:1024
	ds_read_b128 v[136:139], v140 offset:2048
	ds_read_b128 v[140:143], v140 offset:3072
	ds_read_b128 v[144:147], v156
	ds_read_b128 v[148:151], v156 offset:1024
	ds_read_b128 v[152:155], v156 offset:2048
	ds_read_b128 v[156:159], v156 offset:3072
	s_add_u32 s26, s34, 0x100000
	s_addc_u32 s27, s35, 0
	s_mov_b32 m0, s51
	v_lshl_add_u64 v[222:223], s[26:27], 0, v[176:177]
	ds_read_b128 v[160:163], v213 offset:32768
	ds_read_b128 v[164:167], v213 offset:33792
	ds_read_b128 v[168:171], v213 offset:34816
	ds_read_b128 v[172:175], v213 offset:35840
	ds_read_b128 v[188:191], v213 offset:36864
	ds_read_b128 v[192:195], v213 offset:37888
	ds_read_b128 v[196:199], v213 offset:38912
	ds_read_b128 v[200:203], v213 offset:39936
	global_load_lds_dwordx4 v[222:223], off
	v_lshl_add_u64 v[222:223], s[26:27], 0, v[178:179]
	s_mov_b32 m0, s76
	s_nop 0
	global_load_lds_dwordx4 v[222:223], off
	s_waitcnt vmcnt(8)
	s_waitcnt lgkmcnt(0)
	s_setprio 1
	s_barrier
	v_mfma_f32_16x16x32_bf16 v[124:127], v[128:131], v[160:163], v[124:127]
	v_mfma_f32_16x16x32_bf16 v[120:123], v[136:139], v[160:163], v[120:123]
	v_mfma_f32_16x16x32_bf16 v[108:111], v[128:131], v[168:171], v[108:111]
	v_mfma_f32_16x16x32_bf16 v[104:107], v[136:139], v[168:171], v[104:107]
	v_mfma_f32_16x16x32_bf16 v[92:95], v[128:131], v[188:191], v[92:95]
	v_mfma_f32_16x16x32_bf16 v[88:91], v[136:139], v[188:191], v[88:91]
	v_mfma_f32_16x16x32_bf16 v[76:79], v[128:131], v[196:199], v[76:79]
	v_mfma_f32_16x16x32_bf16 v[72:75], v[136:139], v[196:199], v[72:75]
	v_mfma_f32_16x16x32_bf16 v[124:127], v[132:135], v[164:167], v[124:127]
	v_mfma_f32_16x16x32_bf16 v[120:123], v[140:143], v[164:167], v[120:123]
	v_mfma_f32_16x16x32_bf16 v[108:111], v[132:135], v[172:175], v[108:111]
	v_mfma_f32_16x16x32_bf16 v[104:107], v[140:143], v[172:175], v[104:107]
	v_mfma_f32_16x16x32_bf16 v[92:95], v[132:135], v[192:195], v[92:95]
	v_mfma_f32_16x16x32_bf16 v[88:91], v[140:143], v[192:195], v[88:91]
	v_mfma_f32_16x16x32_bf16 v[76:79], v[132:135], v[200:203], v[76:79]
	v_mfma_f32_16x16x32_bf16 v[72:75], v[140:143], v[200:203], v[72:75]
	s_setprio 0
	s_setprio 1
	v_mfma_f32_16x16x32_bf16 v[116:119], v[144:147], v[160:163], v[116:119]
	v_mfma_f32_16x16x32_bf16 v[112:115], v[152:155], v[160:163], v[112:115]
	v_mfma_f32_16x16x32_bf16 v[100:103], v[144:147], v[168:171], v[100:103]
	v_mfma_f32_16x16x32_bf16 v[96:99], v[152:155], v[168:171], v[96:99]
	v_mfma_f32_16x16x32_bf16 v[84:87], v[144:147], v[188:191], v[84:87]
	v_mfma_f32_16x16x32_bf16 v[80:83], v[152:155], v[188:191], v[80:83]
	v_mfma_f32_16x16x32_bf16 v[68:71], v[144:147], v[196:199], v[68:71]
	v_mfma_f32_16x16x32_bf16 v[64:67], v[152:155], v[196:199], v[64:67]
	v_mfma_f32_16x16x32_bf16 v[116:119], v[148:151], v[164:167], v[116:119]
	v_mfma_f32_16x16x32_bf16 v[112:115], v[156:159], v[164:167], v[112:115]
	v_mfma_f32_16x16x32_bf16 v[100:103], v[148:151], v[172:175], v[100:103]
	v_mfma_f32_16x16x32_bf16 v[96:99], v[156:159], v[172:175], v[96:99]
	v_mfma_f32_16x16x32_bf16 v[84:87], v[148:151], v[192:195], v[84:87]
	v_mfma_f32_16x16x32_bf16 v[80:83], v[156:159], v[192:195], v[80:83]
	v_mfma_f32_16x16x32_bf16 v[68:71], v[148:151], v[200:203], v[68:71]
	v_mfma_f32_16x16x32_bf16 v[64:67], v[156:159], v[200:203], v[64:67]
	s_barrier
	s_setprio 0
	s_add_i32 s26, s93, s41
	v_lshl_add_u64 v[204:205], v[204:205], 0, s[10:11]
	s_mov_b32 m0, s26
	ds_read_b128 v[160:163], v213 offset:49152
	ds_read_b128 v[164:167], v213 offset:50176
	ds_read_b128 v[168:171], v213 offset:51200
	ds_read_b128 v[172:175], v213 offset:52224
	ds_read_b128 v[188:191], v213 offset:53248
	ds_read_b128 v[192:195], v213 offset:54272
	ds_read_b128 v[196:199], v213 offset:55296
	ds_read_b128 v[200:203], v213 offset:56320
	global_load_lds_dwordx4 v[204:205], off
	s_add_i32 m0, s26, 0x2000
	s_add_u32 s26, s30, 0x100080
	v_lshl_add_u64 v[204:205], v[216:217], 0, s[10:11]
	s_addc_u32 s27, s31, 0
	s_add_i32 s30, s94, s41
	global_load_lds_dwordx4 v[204:205], off
	v_lshl_add_u64 v[204:205], s[26:27], 0, v[176:177]
	s_mov_b32 m0, s30
	s_nop 0
	global_load_lds_dwordx4 v[204:205], off
	v_lshl_add_u64 v[204:205], s[26:27], 0, v[178:179]
	s_add_i32 m0, s30, 0x2000
	s_nop 0
	global_load_lds_dwordx4 v[204:205], off
	v_lshl_add_u64 v[204:205], v[218:219], 0, s[10:11]
	s_mov_b32 m0, s78
	s_nop 0
	global_load_lds_dwordx4 v[204:205], off
	v_lshl_add_u64 v[204:205], v[220:221], 0, s[10:11]
	s_mov_b32 m0, s79
	s_nop 0
	global_load_lds_dwordx4 v[204:205], off
	s_waitcnt vmcnt(8)
	s_waitcnt lgkmcnt(0)
	s_setprio 1
	s_barrier
	v_mfma_f32_16x16x32_bf16 v[60:63], v[128:131], v[160:163], v[60:63]
	v_mfma_f32_16x16x32_bf16 v[56:59], v[136:139], v[160:163], v[56:59]
	v_mfma_f32_16x16x32_bf16 v[44:47], v[128:131], v[168:171], v[44:47]
	v_mfma_f32_16x16x32_bf16 v[40:43], v[136:139], v[168:171], v[40:43]
	v_mfma_f32_16x16x32_bf16 v[28:31], v[128:131], v[188:191], v[28:31]
	v_mfma_f32_16x16x32_bf16 v[24:27], v[136:139], v[188:191], v[24:27]
	v_mfma_f32_16x16x32_bf16 v[12:15], v[128:131], v[196:199], v[12:15]
	v_mfma_f32_16x16x32_bf16 v[8:11], v[136:139], v[196:199], v[8:11]
	v_mfma_f32_16x16x32_bf16 v[60:63], v[132:135], v[164:167], v[60:63]
	v_mfma_f32_16x16x32_bf16 v[56:59], v[140:143], v[164:167], v[56:59]
	v_mfma_f32_16x16x32_bf16 v[44:47], v[132:135], v[172:175], v[44:47]
	v_mfma_f32_16x16x32_bf16 v[40:43], v[140:143], v[172:175], v[40:43]
	v_mfma_f32_16x16x32_bf16 v[28:31], v[132:135], v[192:195], v[28:31]
	v_mfma_f32_16x16x32_bf16 v[24:27], v[140:143], v[192:195], v[24:27]
	v_mfma_f32_16x16x32_bf16 v[12:15], v[132:135], v[200:203], v[12:15]
	v_mfma_f32_16x16x32_bf16 v[8:11], v[140:143], v[200:203], v[8:11]
	s_setprio 0
	s_setprio 1
	v_mfma_f32_16x16x32_bf16 v[52:55], v[144:147], v[160:163], v[52:55]
	v_mfma_f32_16x16x32_bf16 v[48:51], v[152:155], v[160:163], v[48:51]
	v_mfma_f32_16x16x32_bf16 v[36:39], v[144:147], v[168:171], v[36:39]
	v_mfma_f32_16x16x32_bf16 v[32:35], v[152:155], v[168:171], v[32:35]
	v_mfma_f32_16x16x32_bf16 v[20:23], v[144:147], v[188:191], v[20:23]
	v_mfma_f32_16x16x32_bf16 v[16:19], v[152:155], v[188:191], v[16:19]
	v_mfma_f32_16x16x32_bf16 v[4:7], v[144:147], v[196:199], v[4:7]
	v_mfma_f32_16x16x32_bf16 v[0:3], v[152:155], v[196:199], v[0:3]
	v_mfma_f32_16x16x32_bf16 v[52:55], v[148:151], v[164:167], v[52:55]
	v_mfma_f32_16x16x32_bf16 v[48:51], v[156:159], v[164:167], v[48:51]
	v_mfma_f32_16x16x32_bf16 v[36:39], v[148:151], v[172:175], v[36:39]
	v_mfma_f32_16x16x32_bf16 v[32:35], v[156:159], v[172:175], v[32:35]
	v_mfma_f32_16x16x32_bf16 v[20:23], v[148:151], v[192:195], v[20:23]
	v_mfma_f32_16x16x32_bf16 v[16:19], v[156:159], v[192:195], v[16:19]
	v_mfma_f32_16x16x32_bf16 v[4:7], v[148:151], v[200:203], v[4:7]
	v_mfma_f32_16x16x32_bf16 v[0:3], v[156:159], v[200:203], v[0:3]
	s_barrier
	s_setprio 0
	s_add_i32 s92, s92, 2
	s_add_u32 s90, s90, 0x100
	s_addc_u32 s91, s91, 0
	s_cmp_gt_u32 s92, 61
	s_mov_b64 s[26:27], s[28:29]

.LBB0_1015:
	s_ashr_i32 s15, s14, 31
	s_lshl_b64 s[16:17], s[14:15], 19
	s_add_u32 s16, s82, s16
	s_addc_u32 s17, s83, s17
	s_and_b64 s[18:19], s[0:1], exec
	s_cselect_b32 s15, s17, s23
	s_cselect_b32 s48, s16, s22
	s_ashr_i32 s13, s12, 31
	s_lshl_b64 s[18:19], s[12:13], 19
	s_add_u32 s18, s30, s18
	s_addc_u32 s19, s31, s19
	s_and_b64 s[26:27], s[0:1], exec
	s_cselect_b32 s13, s19, s25
	s_cselect_b32 s49, s18, s24
	s_add_u32 s22, s22, 0x40080
	s_addc_u32 s23, s23, 0
	s_add_u32 s50, s24, 0x100
	s_addc_u32 s51, s25, 0
	s_mov_b32 s52, -2
	s_nop 0
	s_nop 0
	s_nop 0
	s_nop 0
	s_nop 0
	s_nop 0
	s_nop 0
	s_nop 0
	s_nop 0
	s_nop 0
	s_nop 0
	s_nop 0
	s_nop 0
	s_nop 0
	s_nop 0
	ds_read_b128 v[144:147], v151
	ds_read_b128 v[156:159], v151 offset:1024
	ds_read_b128 v[160:163], v151 offset:2048
	ds_read_b128 v[164:167], v151 offset:3072
	ds_read_b128 v[168:171], v152
	ds_read_b128 v[172:175], v152 offset:1024
	ds_read_b128 v[176:179], v152 offset:2048
	ds_read_b128 v[180:183], v152 offset:3072
	s_add_u32 s24, s22, 0xfffc0080
	s_addc_u32 s25, s23, -1
	s_cmp_eq_u32 s52, 12
	s_cselect_b32 s27, s15, s25
	s_cselect_b32 s26, s48, s24
	s_cselect_b32 s25, s13, s51
	s_cselect_b32 s24, s49, s50
	v_lshl_add_u64 v[204:205], s[22:23], 0, v[136:137]
	s_add_i32 m0, s21, 0xc000
	ds_read_b128 v[184:187], v153
	ds_read_b128 v[188:191], v153 offset:1024
	ds_read_b128 v[192:195], v153 offset:2048
	ds_read_b128 v[196:199], v153 offset:3072
	ds_read_b128 v[200:203], v153 offset:4096
	ds_read_b128 v[208:211], v153 offset:5120
	ds_read_b128 v[212:215], v153 offset:6144
	ds_read_b128 v[216:219], v153 offset:7168
	global_load_lds_dwordx4 v[204:205], off
	v_lshl_add_u64 v[204:205], s[22:23], 0, v[138:139]
	s_add_i32 m0, s21, 0xe000
	s_nop 0
	global_load_lds_dwordx4 v[204:205], off
	s_waitcnt vmcnt(8)
	s_waitcnt lgkmcnt(0)
	s_setprio 1
	s_barrier
	v_mfma_f32_16x16x32_bf16 v[124:127], v[144:147], v[184:187], 0
	v_mfma_f32_16x16x32_bf16 v[120:123], v[160:163], v[184:187], 0
	v_mfma_f32_16x16x32_bf16 v[116:119], v[144:147], v[192:195], 0
	v_mfma_f32_16x16x32_bf16 v[112:115], v[160:163], v[192:195], 0
	v_mfma_f32_16x16x32_bf16 v[104:107], v[144:147], v[200:203], 0
	v_mfma_f32_16x16x32_bf16 v[96:99], v[160:163], v[200:203], 0
	v_mfma_f32_16x16x32_bf16 v[76:79], v[144:147], v[212:215], 0
	v_mfma_f32_16x16x32_bf16 v[72:75], v[160:163], v[212:215], 0
	v_mfma_f32_16x16x32_bf16 v[124:127], v[156:159], v[188:191], v[124:127]
	v_mfma_f32_16x16x32_bf16 v[120:123], v[164:167], v[188:191], v[120:123]
	v_mfma_f32_16x16x32_bf16 v[116:119], v[156:159], v[196:199], v[116:119]
	v_mfma_f32_16x16x32_bf16 v[112:115], v[164:167], v[196:199], v[112:115]
	v_mfma_f32_16x16x32_bf16 v[104:107], v[156:159], v[208:211], v[104:107]
	v_mfma_f32_16x16x32_bf16 v[96:99], v[164:167], v[208:211], v[96:99]
	v_mfma_f32_16x16x32_bf16 v[76:79], v[156:159], v[216:219], v[76:79]
	v_mfma_f32_16x16x32_bf16 v[72:75], v[164:167], v[216:219], v[72:75]
	s_setprio 0
	s_setprio 1
	v_mfma_f32_16x16x32_bf16 v[108:111], v[168:171], v[184:187], 0
	v_mfma_f32_16x16x32_bf16 v[100:103], v[176:179], v[184:187], 0
	v_mfma_f32_16x16x32_bf16 v[92:95], v[168:171], v[192:195], 0
	v_mfma_f32_16x16x32_bf16 v[88:91], v[176:179], v[192:195], 0
	v_mfma_f32_16x16x32_bf16 v[84:87], v[168:171], v[200:203], 0
	v_mfma_f32_16x16x32_bf16 v[80:83], v[176:179], v[200:203], 0
	v_mfma_f32_16x16x32_bf16 v[68:71], v[168:171], v[212:215], 0
	v_mfma_f32_16x16x32_bf16 v[64:67], v[176:179], v[212:215], 0
	v_mfma_f32_16x16x32_bf16 v[108:111], v[172:175], v[188:191], v[108:111]
	v_mfma_f32_16x16x32_bf16 v[100:103], v[180:183], v[188:191], v[100:103]
	v_mfma_f32_16x16x32_bf16 v[92:95], v[172:175], v[196:199], v[92:95]
	v_mfma_f32_16x16x32_bf16 v[88:91], v[180:183], v[196:199], v[88:91]
	v_mfma_f32_16x16x32_bf16 v[84:87], v[172:175], v[208:211], v[84:87]
	v_mfma_f32_16x16x32_bf16 v[80:83], v[180:183], v[208:211], v[80:83]
	v_mfma_f32_16x16x32_bf16 v[68:71], v[172:175], v[216:219], v[68:71]
	v_mfma_f32_16x16x32_bf16 v[64:67], v[180:183], v[216:219], v[64:67]
	s_barrier
	s_setprio 0
	s_add_i32 s53, s43, s33
	v_lshl_add_u64 v[204:205], s[24:25], 0, v[132:133]
	s_mov_b32 m0, s53
	ds_read_b128 v[184:187], v153 offset:16384
	ds_read_b128 v[188:191], v153 offset:17408
	ds_read_b128 v[192:195], v153 offset:18432
	ds_read_b128 v[196:199], v153 offset:19456
	ds_read_b128 v[200:203], v153 offset:20480
	ds_read_b128 v[208:211], v153 offset:21504
	ds_read_b128 v[212:215], v153 offset:22528
	ds_read_b128 v[216:219], v153 offset:23552
	global_load_lds_dwordx4 v[204:205], off
	s_add_i32 m0, s53, 0x2000
	s_add_u32 s54, s24, 0x40000
	v_lshl_add_u64 v[220:221], s[24:25], 0, v[128:129]
	s_addc_u32 s55, s25, 0
	s_add_i32 s53, s44, s33
	global_load_lds_dwordx4 v[220:221], off
	v_lshl_add_u64 v[222:223], s[54:55], 0, v[132:133]
	s_mov_b32 m0, s53
	v_lshl_add_u64 v[224:225], s[26:27], 0, v[130:131]
	global_load_lds_dwordx4 v[222:223], off
	v_lshl_add_u64 v[222:223], s[54:55], 0, v[128:129]
	s_add_i32 m0, s53, 0x2000
	s_nop 0
	global_load_lds_dwordx4 v[222:223], off
	v_lshl_add_u64 v[222:223], s[26:27], 0, v[134:135]
	s_mov_b32 m0, s21
	s_nop 0
	global_load_lds_dwordx4 v[222:223], off
	s_mov_b32 m0, s36
	s_nop 0
	global_load_lds_dwordx4 v[224:225], off
	s_waitcnt vmcnt(8)
	s_waitcnt lgkmcnt(0)
	s_setprio 1
	s_barrier
	v_mfma_f32_16x16x32_bf16 v[60:63], v[144:147], v[184:187], 0
	v_mfma_f32_16x16x32_bf16 v[56:59], v[160:163], v[184:187], 0
	v_mfma_f32_16x16x32_bf16 v[44:47], v[144:147], v[192:195], 0
	v_mfma_f32_16x16x32_bf16 v[40:43], v[160:163], v[192:195], 0
	v_mfma_f32_16x16x32_bf16 v[28:31], v[144:147], v[200:203], 0
	v_mfma_f32_16x16x32_bf16 v[24:27], v[160:163], v[200:203], 0
	v_mfma_f32_16x16x32_bf16 v[12:15], v[144:147], v[212:215], 0
	v_mfma_f32_16x16x32_bf16 v[8:11], v[160:163], v[212:215], 0
	v_mfma_f32_16x16x32_bf16 v[60:63], v[156:159], v[188:191], v[60:63]
	v_mfma_f32_16x16x32_bf16 v[56:59], v[164:167], v[188:191], v[56:59]
	v_mfma_f32_16x16x32_bf16 v[44:47], v[156:159], v[196:199], v[44:47]
	v_mfma_f32_16x16x32_bf16 v[40:43], v[164:167], v[196:199], v[40:43]
	v_mfma_f32_16x16x32_bf16 v[28:31], v[156:159], v[208:211], v[28:31]
	v_mfma_f32_16x16x32_bf16 v[24:27], v[164:167], v[208:211], v[24:27]
	v_mfma_f32_16x16x32_bf16 v[12:15], v[156:159], v[216:219], v[12:15]
	v_mfma_f32_16x16x32_bf16 v[8:11], v[164:167], v[216:219], v[8:11]
	s_setprio 0
	s_setprio 1
	v_mfma_f32_16x16x32_bf16 v[52:55], v[168:171], v[184:187], 0
	v_mfma_f32_16x16x32_bf16 v[48:51], v[176:179], v[184:187], 0
	v_mfma_f32_16x16x32_bf16 v[36:39], v[168:171], v[192:195], 0
	v_mfma_f32_16x16x32_bf16 v[32:35], v[176:179], v[192:195], 0
	v_mfma_f32_16x16x32_bf16 v[20:23], v[168:171], v[200:203], 0
	v_mfma_f32_16x16x32_bf16 v[16:19], v[176:179], v[200:203], 0
	v_mfma_f32_16x16x32_bf16 v[4:7], v[168:171], v[212:215], 0
	v_mfma_f32_16x16x32_bf16 v[0:3], v[176:179], v[212:215], 0
	v_mfma_f32_16x16x32_bf16 v[52:55], v[172:175], v[188:191], v[52:55]
	v_mfma_f32_16x16x32_bf16 v[48:51], v[180:183], v[188:191], v[48:51]
	v_mfma_f32_16x16x32_bf16 v[36:39], v[172:175], v[196:199], v[36:39]
	v_mfma_f32_16x16x32_bf16 v[32:35], v[180:183], v[196:199], v[32:35]
	v_mfma_f32_16x16x32_bf16 v[20:23], v[172:175], v[208:211], v[20:23]
	v_mfma_f32_16x16x32_bf16 v[16:19], v[180:183], v[208:211], v[16:19]
	v_mfma_f32_16x16x32_bf16 v[4:7], v[172:175], v[216:219], v[4:7]
	v_mfma_f32_16x16x32_bf16 v[0:3], v[180:183], v[216:219], v[0:3]
	s_barrier
	s_setprio 0
	s_add_i32 s53, 0, 0x18000
	s_add_i32 s54, 0, 0x1c000
	v_add_u32_e32 v164, s53, v149
	v_add_u32_e32 v180, s54, v149
	ds_read_b128 v[144:147], v164
	ds_read_b128 v[156:159], v164 offset:1024
	ds_read_b128 v[160:163], v164 offset:2048
	ds_read_b128 v[164:167], v164 offset:3072
	ds_read_b128 v[168:171], v180
	ds_read_b128 v[172:175], v180 offset:1024
	ds_read_b128 v[176:179], v180 offset:2048
	ds_read_b128 v[180:183], v180 offset:3072
	s_add_u32 s26, s26, 0x40000
	s_addc_u32 s27, s27, 0
	s_mov_b32 m0, s37
	v_lshl_add_u64 v[226:227], s[26:27], 0, v[134:135]
	ds_read_b128 v[184:187], v153 offset:32768
	ds_read_b128 v[188:191], v153 offset:33792
	ds_read_b128 v[192:195], v153 offset:34816
	ds_read_b128 v[196:199], v153 offset:35840
	ds_read_b128 v[200:203], v153 offset:36864
	ds_read_b128 v[208:211], v153 offset:37888
	ds_read_b128 v[212:215], v153 offset:38912
	ds_read_b128 v[216:219], v153 offset:39936
	global_load_lds_dwordx4 v[226:227], off
	v_lshl_add_u64 v[226:227], s[26:27], 0, v[130:131]
	s_mov_b32 m0, s38
	s_nop 0
	global_load_lds_dwordx4 v[226:227], off
	s_waitcnt vmcnt(8)
	s_waitcnt lgkmcnt(0)
	s_setprio 1
	s_barrier
	v_mfma_f32_16x16x32_bf16 v[124:127], v[144:147], v[184:187], v[124:127]
	v_mfma_f32_16x16x32_bf16 v[120:123], v[160:163], v[184:187], v[120:123]
	v_mfma_f32_16x16x32_bf16 v[116:119], v[144:147], v[192:195], v[116:119]
	v_mfma_f32_16x16x32_bf16 v[112:115], v[160:163], v[192:195], v[112:115]
	v_mfma_f32_16x16x32_bf16 v[104:107], v[144:147], v[200:203], v[104:107]
	v_mfma_f32_16x16x32_bf16 v[96:99], v[160:163], v[200:203], v[96:99]
	v_mfma_f32_16x16x32_bf16 v[76:79], v[144:147], v[212:215], v[76:79]
	v_mfma_f32_16x16x32_bf16 v[72:75], v[160:163], v[212:215], v[72:75]
	v_mfma_f32_16x16x32_bf16 v[124:127], v[156:159], v[188:191], v[124:127]
	v_mfma_f32_16x16x32_bf16 v[120:123], v[164:167], v[188:191], v[120:123]
	v_mfma_f32_16x16x32_bf16 v[116:119], v[156:159], v[196:199], v[116:119]
	v_mfma_f32_16x16x32_bf16 v[112:115], v[164:167], v[196:199], v[112:115]
	v_mfma_f32_16x16x32_bf16 v[104:107], v[156:159], v[208:211], v[104:107]
	v_mfma_f32_16x16x32_bf16 v[96:99], v[164:167], v[208:211], v[96:99]
	v_mfma_f32_16x16x32_bf16 v[76:79], v[156:159], v[216:219], v[76:79]
	v_mfma_f32_16x16x32_bf16 v[72:75], v[164:167], v[216:219], v[72:75]
	s_setprio 0
	s_setprio 1
	v_mfma_f32_16x16x32_bf16 v[108:111], v[168:171], v[184:187], v[108:111]
	v_mfma_f32_16x16x32_bf16 v[100:103], v[176:179], v[184:187], v[100:103]
	v_mfma_f32_16x16x32_bf16 v[92:95], v[168:171], v[192:195], v[92:95]
	v_mfma_f32_16x16x32_bf16 v[88:91], v[176:179], v[192:195], v[88:91]
	v_mfma_f32_16x16x32_bf16 v[84:87], v[168:171], v[200:203], v[84:87]
	v_mfma_f32_16x16x32_bf16 v[80:83], v[176:179], v[200:203], v[80:83]
	v_mfma_f32_16x16x32_bf16 v[68:71], v[168:171], v[212:215], v[68:71]
	v_mfma_f32_16x16x32_bf16 v[64:67], v[176:179], v[212:215], v[64:67]
	v_mfma_f32_16x16x32_bf16 v[108:111], v[172:175], v[188:191], v[108:111]
	v_mfma_f32_16x16x32_bf16 v[100:103], v[180:183], v[188:191], v[100:103]
	v_mfma_f32_16x16x32_bf16 v[92:95], v[172:175], v[196:199], v[92:95]
	v_mfma_f32_16x16x32_bf16 v[88:91], v[180:183], v[196:199], v[88:91]
	v_mfma_f32_16x16x32_bf16 v[84:87], v[172:175], v[208:211], v[84:87]
	v_mfma_f32_16x16x32_bf16 v[80:83], v[180:183], v[208:211], v[80:83]
	v_mfma_f32_16x16x32_bf16 v[68:71], v[172:175], v[216:219], v[68:71]
	v_mfma_f32_16x16x32_bf16 v[64:67], v[180:183], v[216:219], v[64:67]
	s_barrier
	s_setprio 0
	s_add_i32 s26, s53, s33
	v_lshl_add_u64 v[204:205], v[204:205], 0, s[8:9]
	s_mov_b32 m0, s26
	ds_read_b128 v[184:187], v153 offset:49152
	ds_read_b128 v[188:191], v153 offset:50176
	ds_read_b128 v[192:195], v153 offset:51200
	ds_read_b128 v[196:199], v153 offset:52224
	ds_read_b128 v[200:203], v153 offset:53248
	ds_read_b128 v[208:211], v153 offset:54272
	ds_read_b128 v[212:215], v153 offset:55296
	ds_read_b128 v[216:219], v153 offset:56320
	global_load_lds_dwordx4 v[204:205], off
	s_add_i32 m0, s26, 0x2000
	s_add_u32 s24, s24, 0x40080
	v_lshl_add_u64 v[204:205], v[220:221], 0, s[8:9]
	s_addc_u32 s25, s25, 0
	s_add_i32 s26, s54, s33
	global_load_lds_dwordx4 v[204:205], off
	v_lshl_add_u64 v[204:205], s[24:25], 0, v[132:133]
	s_mov_b32 m0, s26
	s_nop 0
	global_load_lds_dwordx4 v[204:205], off
	v_lshl_add_u64 v[204:205], s[24:25], 0, v[128:129]
	s_add_i32 m0, s26, 0x2000
	s_nop 0
	global_load_lds_dwordx4 v[204:205], off
	v_lshl_add_u64 v[204:205], v[222:223], 0, s[8:9]
	s_mov_b32 m0, s40
	s_nop 0
	global_load_lds_dwordx4 v[204:205], off
	v_lshl_add_u64 v[204:205], v[224:225], 0, s[8:9]
	s_mov_b32 m0, s41
	s_nop 0
	global_load_lds_dwordx4 v[204:205], off
	s_waitcnt vmcnt(8)
	s_waitcnt lgkmcnt(0)
	s_setprio 1
	s_barrier
	v_mfma_f32_16x16x32_bf16 v[60:63], v[144:147], v[184:187], v[60:63]
	v_mfma_f32_16x16x32_bf16 v[56:59], v[160:163], v[184:187], v[56:59]
	v_mfma_f32_16x16x32_bf16 v[44:47], v[144:147], v[192:195], v[44:47]
	v_mfma_f32_16x16x32_bf16 v[40:43], v[160:163], v[192:195], v[40:43]
	v_mfma_f32_16x16x32_bf16 v[28:31], v[144:147], v[200:203], v[28:31]
	v_mfma_f32_16x16x32_bf16 v[24:27], v[160:163], v[200:203], v[24:27]
	v_mfma_f32_16x16x32_bf16 v[12:15], v[144:147], v[212:215], v[12:15]
	v_mfma_f32_16x16x32_bf16 v[8:11], v[160:163], v[212:215], v[8:11]
	v_mfma_f32_16x16x32_bf16 v[60:63], v[156:159], v[188:191], v[60:63]
	v_mfma_f32_16x16x32_bf16 v[56:59], v[164:167], v[188:191], v[56:59]
	v_mfma_f32_16x16x32_bf16 v[44:47], v[156:159], v[196:199], v[44:47]
	v_mfma_f32_16x16x32_bf16 v[40:43], v[164:167], v[196:199], v[40:43]
	v_mfma_f32_16x16x32_bf16 v[28:31], v[156:159], v[208:211], v[28:31]
	v_mfma_f32_16x16x32_bf16 v[24:27], v[164:167], v[208:211], v[24:27]
	v_mfma_f32_16x16x32_bf16 v[12:15], v[156:159], v[216:219], v[12:15]
	v_mfma_f32_16x16x32_bf16 v[8:11], v[164:167], v[216:219], v[8:11]
	s_setprio 0
	s_setprio 1
	v_mfma_f32_16x16x32_bf16 v[52:55], v[168:171], v[184:187], v[52:55]
	v_mfma_f32_16x16x32_bf16 v[48:51], v[176:179], v[184:187], v[48:51]
	v_mfma_f32_16x16x32_bf16 v[36:39], v[168:171], v[192:195], v[36:39]
	v_mfma_f32_16x16x32_bf16 v[32:35], v[176:179], v[192:195], v[32:35]
	v_mfma_f32_16x16x32_bf16 v[20:23], v[168:171], v[200:203], v[20:23]
	v_mfma_f32_16x16x32_bf16 v[16:19], v[176:179], v[200:203], v[16:19]
	v_mfma_f32_16x16x32_bf16 v[4:7], v[168:171], v[212:215], v[4:7]
	v_mfma_f32_16x16x32_bf16 v[0:3], v[176:179], v[212:215], v[0:3]
	v_mfma_f32_16x16x32_bf16 v[52:55], v[172:175], v[188:191], v[52:55]
	v_mfma_f32_16x16x32_bf16 v[48:51], v[180:183], v[188:191], v[48:51]
	v_mfma_f32_16x16x32_bf16 v[36:39], v[172:175], v[196:199], v[36:39]
	v_mfma_f32_16x16x32_bf16 v[32:35], v[180:183], v[196:199], v[32:35]
	v_mfma_f32_16x16x32_bf16 v[20:23], v[172:175], v[208:211], v[20:23]
	v_mfma_f32_16x16x32_bf16 v[16:19], v[180:183], v[208:211], v[16:19]
	v_mfma_f32_16x16x32_bf16 v[4:7], v[172:175], v[216:219], v[4:7]
	v_mfma_f32_16x16x32_bf16 v[0:3], v[180:183], v[216:219], v[0:3]
	s_barrier
	s_setprio 0
	s_add_i32 s52, s52, 2
	s_add_u32 s22, s22, 0x100
	s_addc_u32 s23, s23, 0
	s_add_u32 s50, s50, 0x100
	s_addc_u32 s51, s51, 0
	s_cmp_gt_u32 s52, 13

.LBB0_1217:
	s_ashr_i32 s17, s16, 31
	s_lshl_b64 s[18:19], s[16:17], 19
	s_add_u32 s18, s84, s18
	s_addc_u32 s19, s85, s19
	s_and_b64 s[20:21], s[4:5], exec
	s_cselect_b32 s3, s19, s27
	s_cselect_b32 s17, s18, s26
	s_ashr_i32 s15, s14, 31
	s_lshl_b64 s[20:21], s[14:15], 19
	s_add_u32 s20, s37, s20
	s_addc_u32 s21, s38, s21
	s_and_b64 s[30:31], s[4:5], exec
	s_cselect_b32 s15, s21, s29
	s_cselect_b32 s23, s20, s28
	s_add_u32 s52, s28, 0x100
	s_addc_u32 s53, s29, 0
	s_mov_b32 s54, -2
	s_waitcnt lgkmcnt(0)
	ds_read_b128 v[128:131], v212
	ds_read_b128 v[132:135], v212 offset:1024
	ds_read_b128 v[136:139], v212 offset:2048
	ds_read_b128 v[140:143], v212 offset:3072
	ds_read_b128 v[144:147], v213
	ds_read_b128 v[148:151], v213 offset:1024
	ds_read_b128 v[152:155], v213 offset:2048
	ds_read_b128 v[156:159], v213 offset:3072
	s_add_u32 s28, s26, 0x100
	s_addc_u32 s29, s27, 0
	s_cmp_eq_u32 s54, 12
	s_cselect_b32 s35, s3, s29
	s_cselect_b32 s34, s17, s28
	s_cselect_b32 s31, s15, s53
	s_cselect_b32 s30, s23, s52
	v_lshl_add_u64 v[204:205], s[26:27], 0, v[180:181]
	s_add_i32 m0, s25, 0xc000
	ds_read_b128 v[160:163], v214
	ds_read_b128 v[164:167], v214 offset:1024
	ds_read_b128 v[168:171], v214 offset:2048
	ds_read_b128 v[172:175], v214 offset:3072
	ds_read_b128 v[188:191], v214 offset:4096
	ds_read_b128 v[192:195], v214 offset:5120
	ds_read_b128 v[196:199], v214 offset:6144
	ds_read_b128 v[200:203], v214 offset:7168
	global_load_lds_dwordx4 v[204:205], off
	v_lshl_add_u64 v[204:205], s[26:27], 0, v[182:183]
	s_add_i32 m0, s25, 0xe000
	s_nop 0
	global_load_lds_dwordx4 v[204:205], off
	s_waitcnt vmcnt(8)
	s_waitcnt lgkmcnt(0)
	s_setprio 1
	s_barrier
	v_mfma_f32_16x16x32_bf16 v[124:127], v[128:131], v[160:163], 0
	v_mfma_f32_16x16x32_bf16 v[120:123], v[136:139], v[160:163], 0
	v_mfma_f32_16x16x32_bf16 v[108:111], v[128:131], v[168:171], 0
	v_mfma_f32_16x16x32_bf16 v[104:107], v[136:139], v[168:171], 0
	v_mfma_f32_16x16x32_bf16 v[92:95], v[128:131], v[188:191], 0
	v_mfma_f32_16x16x32_bf16 v[88:91], v[136:139], v[188:191], 0
	v_mfma_f32_16x16x32_bf16 v[76:79], v[128:131], v[196:199], 0
	v_mfma_f32_16x16x32_bf16 v[72:75], v[136:139], v[196:199], 0
	v_mfma_f32_16x16x32_bf16 v[124:127], v[132:135], v[164:167], v[124:127]
	v_mfma_f32_16x16x32_bf16 v[120:123], v[140:143], v[164:167], v[120:123]
	v_mfma_f32_16x16x32_bf16 v[108:111], v[132:135], v[172:175], v[108:111]
	v_mfma_f32_16x16x32_bf16 v[104:107], v[140:143], v[172:175], v[104:107]
	v_mfma_f32_16x16x32_bf16 v[92:95], v[132:135], v[192:195], v[92:95]
	v_mfma_f32_16x16x32_bf16 v[88:91], v[140:143], v[192:195], v[88:91]
	v_mfma_f32_16x16x32_bf16 v[76:79], v[132:135], v[200:203], v[76:79]
	v_mfma_f32_16x16x32_bf16 v[72:75], v[140:143], v[200:203], v[72:75]
	s_setprio 0
	s_setprio 1
	v_mfma_f32_16x16x32_bf16 v[116:119], v[144:147], v[160:163], 0
	v_mfma_f32_16x16x32_bf16 v[112:115], v[152:155], v[160:163], 0
	v_mfma_f32_16x16x32_bf16 v[100:103], v[144:147], v[168:171], 0
	v_mfma_f32_16x16x32_bf16 v[96:99], v[152:155], v[168:171], 0
	v_mfma_f32_16x16x32_bf16 v[84:87], v[144:147], v[188:191], 0
	v_mfma_f32_16x16x32_bf16 v[80:83], v[152:155], v[188:191], 0
	v_mfma_f32_16x16x32_bf16 v[68:71], v[144:147], v[196:199], 0
	v_mfma_f32_16x16x32_bf16 v[64:67], v[152:155], v[196:199], 0
	v_mfma_f32_16x16x32_bf16 v[116:119], v[148:151], v[164:167], v[116:119]
	v_mfma_f32_16x16x32_bf16 v[112:115], v[156:159], v[164:167], v[112:115]
	v_mfma_f32_16x16x32_bf16 v[100:103], v[148:151], v[172:175], v[100:103]
	v_mfma_f32_16x16x32_bf16 v[96:99], v[156:159], v[172:175], v[96:99]
	v_mfma_f32_16x16x32_bf16 v[84:87], v[148:151], v[192:195], v[84:87]
	v_mfma_f32_16x16x32_bf16 v[80:83], v[156:159], v[192:195], v[80:83]
	v_mfma_f32_16x16x32_bf16 v[68:71], v[148:151], v[200:203], v[68:71]
	v_mfma_f32_16x16x32_bf16 v[64:67], v[156:159], v[200:203], v[64:67]
	s_barrier
	s_setprio 0
	s_add_i32 s26, s50, s39
	v_lshl_add_u64 v[204:205], s[30:31], 0, v[176:177]
	s_mov_b32 m0, s26
	ds_read_b128 v[160:163], v214 offset:16384
	ds_read_b128 v[164:167], v214 offset:17408
	ds_read_b128 v[168:171], v214 offset:18432
	ds_read_b128 v[172:175], v214 offset:19456
	ds_read_b128 v[188:191], v214 offset:20480
	ds_read_b128 v[192:195], v214 offset:21504
	ds_read_b128 v[196:199], v214 offset:22528
	ds_read_b128 v[200:203], v214 offset:23552
	global_load_lds_dwordx4 v[204:205], off
	s_add_i32 m0, s26, 0x2000
	s_add_u32 s26, s30, 0x40000
	v_lshl_add_u64 v[216:217], s[30:31], 0, v[178:179]
	s_addc_u32 s27, s31, 0
	s_add_i32 s55, s51, s39
	global_load_lds_dwordx4 v[216:217], off
	v_lshl_add_u64 v[218:219], s[26:27], 0, v[176:177]
	s_mov_b32 m0, s55
	v_lshl_add_u64 v[220:221], s[34:35], 0, v[178:179]
	global_load_lds_dwordx4 v[218:219], off
	v_lshl_add_u64 v[218:219], s[26:27], 0, v[178:179]
	s_add_i32 m0, s55, 0x2000
	s_nop 0
	global_load_lds_dwordx4 v[218:219], off
	v_lshl_add_u64 v[218:219], s[34:35], 0, v[176:177]
	s_mov_b32 m0, s25
	s_nop 0
	global_load_lds_dwordx4 v[218:219], off
	s_mov_b32 m0, s40
	s_nop 0
	global_load_lds_dwordx4 v[220:221], off
	s_waitcnt vmcnt(8)
	s_waitcnt lgkmcnt(0)
	s_setprio 1
	s_barrier
	v_mfma_f32_16x16x32_bf16 v[60:63], v[128:131], v[160:163], 0
	v_mfma_f32_16x16x32_bf16 v[56:59], v[136:139], v[160:163], 0
	v_mfma_f32_16x16x32_bf16 v[44:47], v[128:131], v[168:171], 0
	v_mfma_f32_16x16x32_bf16 v[40:43], v[136:139], v[168:171], 0
	v_mfma_f32_16x16x32_bf16 v[28:31], v[128:131], v[188:191], 0
	v_mfma_f32_16x16x32_bf16 v[24:27], v[136:139], v[188:191], 0
	v_mfma_f32_16x16x32_bf16 v[12:15], v[128:131], v[196:199], 0
	v_mfma_f32_16x16x32_bf16 v[8:11], v[136:139], v[196:199], 0
	v_mfma_f32_16x16x32_bf16 v[60:63], v[132:135], v[164:167], v[60:63]
	v_mfma_f32_16x16x32_bf16 v[56:59], v[140:143], v[164:167], v[56:59]
	v_mfma_f32_16x16x32_bf16 v[44:47], v[132:135], v[172:175], v[44:47]
	v_mfma_f32_16x16x32_bf16 v[40:43], v[140:143], v[172:175], v[40:43]
	v_mfma_f32_16x16x32_bf16 v[28:31], v[132:135], v[192:195], v[28:31]
	v_mfma_f32_16x16x32_bf16 v[24:27], v[140:143], v[192:195], v[24:27]
	v_mfma_f32_16x16x32_bf16 v[12:15], v[132:135], v[200:203], v[12:15]
	v_mfma_f32_16x16x32_bf16 v[8:11], v[140:143], v[200:203], v[8:11]
	s_setprio 0
	s_setprio 1
	v_mfma_f32_16x16x32_bf16 v[52:55], v[144:147], v[160:163], 0
	v_mfma_f32_16x16x32_bf16 v[48:51], v[152:155], v[160:163], 0
	v_mfma_f32_16x16x32_bf16 v[36:39], v[144:147], v[168:171], 0
	v_mfma_f32_16x16x32_bf16 v[32:35], v[152:155], v[168:171], 0
	v_mfma_f32_16x16x32_bf16 v[20:23], v[144:147], v[188:191], 0
	v_mfma_f32_16x16x32_bf16 v[16:19], v[152:155], v[188:191], 0
	v_mfma_f32_16x16x32_bf16 v[4:7], v[144:147], v[196:199], 0
	v_mfma_f32_16x16x32_bf16 v[0:3], v[152:155], v[196:199], 0
	v_mfma_f32_16x16x32_bf16 v[52:55], v[148:151], v[164:167], v[52:55]
	v_mfma_f32_16x16x32_bf16 v[48:51], v[156:159], v[164:167], v[48:51]
	v_mfma_f32_16x16x32_bf16 v[36:39], v[148:151], v[172:175], v[36:39]
	v_mfma_f32_16x16x32_bf16 v[32:35], v[156:159], v[172:175], v[32:35]
	v_mfma_f32_16x16x32_bf16 v[20:23], v[148:151], v[192:195], v[20:23]
	v_mfma_f32_16x16x32_bf16 v[16:19], v[156:159], v[192:195], v[16:19]
	v_mfma_f32_16x16x32_bf16 v[4:7], v[148:151], v[200:203], v[4:7]
	v_mfma_f32_16x16x32_bf16 v[0:3], v[156:159], v[200:203], v[0:3]
	s_barrier
	s_setprio 0
	s_add_i32 s55, 0, 0x18000
	s_add_i32 s56, 0, 0x1c000
	v_add_u32_e32 v140, s55, v210
	v_add_u32_e32 v156, s56, v210
	ds_read_b128 v[128:131], v140
	ds_read_b128 v[132:135], v140 offset:1024
	ds_read_b128 v[136:139], v140 offset:2048
	ds_read_b128 v[140:143], v140 offset:3072
	ds_read_b128 v[144:147], v156
	ds_read_b128 v[148:151], v156 offset:1024
	ds_read_b128 v[152:155], v156 offset:2048
	ds_read_b128 v[156:159], v156 offset:3072
	s_add_u32 s26, s34, 0x40000
	s_addc_u32 s27, s35, 0
	s_mov_b32 m0, s41
	v_lshl_add_u64 v[222:223], s[26:27], 0, v[176:177]
	ds_read_b128 v[160:163], v214 offset:32768
	ds_read_b128 v[164:167], v214 offset:33792
	ds_read_b128 v[168:171], v214 offset:34816
	ds_read_b128 v[172:175], v214 offset:35840
	ds_read_b128 v[188:191], v214 offset:36864
	ds_read_b128 v[192:195], v214 offset:37888
	ds_read_b128 v[196:199], v214 offset:38912
	ds_read_b128 v[200:203], v214 offset:39936
	global_load_lds_dwordx4 v[222:223], off
	v_lshl_add_u64 v[222:223], s[26:27], 0, v[178:179]
	s_mov_b32 m0, s42
	s_nop 0
	global_load_lds_dwordx4 v[222:223], off
	s_waitcnt vmcnt(8)
	s_waitcnt lgkmcnt(0)
	s_setprio 1
	s_barrier
	v_mfma_f32_16x16x32_bf16 v[124:127], v[128:131], v[160:163], v[124:127]
	v_mfma_f32_16x16x32_bf16 v[120:123], v[136:139], v[160:163], v[120:123]
	v_mfma_f32_16x16x32_bf16 v[108:111], v[128:131], v[168:171], v[108:111]
	v_mfma_f32_16x16x32_bf16 v[104:107], v[136:139], v[168:171], v[104:107]
	v_mfma_f32_16x16x32_bf16 v[92:95], v[128:131], v[188:191], v[92:95]
	v_mfma_f32_16x16x32_bf16 v[88:91], v[136:139], v[188:191], v[88:91]
	v_mfma_f32_16x16x32_bf16 v[76:79], v[128:131], v[196:199], v[76:79]
	v_mfma_f32_16x16x32_bf16 v[72:75], v[136:139], v[196:199], v[72:75]
	v_mfma_f32_16x16x32_bf16 v[124:127], v[132:135], v[164:167], v[124:127]
	v_mfma_f32_16x16x32_bf16 v[120:123], v[140:143], v[164:167], v[120:123]
	v_mfma_f32_16x16x32_bf16 v[108:111], v[132:135], v[172:175], v[108:111]
	v_mfma_f32_16x16x32_bf16 v[104:107], v[140:143], v[172:175], v[104:107]
	v_mfma_f32_16x16x32_bf16 v[92:95], v[132:135], v[192:195], v[92:95]
	v_mfma_f32_16x16x32_bf16 v[88:91], v[140:143], v[192:195], v[88:91]
	v_mfma_f32_16x16x32_bf16 v[76:79], v[132:135], v[200:203], v[76:79]
	v_mfma_f32_16x16x32_bf16 v[72:75], v[140:143], v[200:203], v[72:75]
	s_setprio 0
	s_setprio 1
	v_mfma_f32_16x16x32_bf16 v[116:119], v[144:147], v[160:163], v[116:119]
	v_mfma_f32_16x16x32_bf16 v[112:115], v[152:155], v[160:163], v[112:115]
	v_mfma_f32_16x16x32_bf16 v[100:103], v[144:147], v[168:171], v[100:103]
	v_mfma_f32_16x16x32_bf16 v[96:99], v[152:155], v[168:171], v[96:99]
	v_mfma_f32_16x16x32_bf16 v[84:87], v[144:147], v[188:191], v[84:87]
	v_mfma_f32_16x16x32_bf16 v[80:83], v[152:155], v[188:191], v[80:83]
	v_mfma_f32_16x16x32_bf16 v[68:71], v[144:147], v[196:199], v[68:71]
	v_mfma_f32_16x16x32_bf16 v[64:67], v[152:155], v[196:199], v[64:67]
	v_mfma_f32_16x16x32_bf16 v[116:119], v[148:151], v[164:167], v[116:119]
	v_mfma_f32_16x16x32_bf16 v[112:115], v[156:159], v[164:167], v[112:115]
	v_mfma_f32_16x16x32_bf16 v[100:103], v[148:151], v[172:175], v[100:103]
	v_mfma_f32_16x16x32_bf16 v[96:99], v[156:159], v[172:175], v[96:99]
	v_mfma_f32_16x16x32_bf16 v[84:87], v[148:151], v[192:195], v[84:87]
	v_mfma_f32_16x16x32_bf16 v[80:83], v[156:159], v[192:195], v[80:83]
	v_mfma_f32_16x16x32_bf16 v[68:71], v[148:151], v[200:203], v[68:71]
	v_mfma_f32_16x16x32_bf16 v[64:67], v[156:159], v[200:203], v[64:67]
	s_barrier
	s_setprio 0
	s_add_i32 s26, s55, s39
	v_lshl_add_u64 v[204:205], v[204:205], 0, s[10:11]
	s_mov_b32 m0, s26
	ds_read_b128 v[160:163], v214 offset:49152
	ds_read_b128 v[164:167], v214 offset:50176
	ds_read_b128 v[168:171], v214 offset:51200
	ds_read_b128 v[172:175], v214 offset:52224
	ds_read_b128 v[188:191], v214 offset:53248
	ds_read_b128 v[192:195], v214 offset:54272
	ds_read_b128 v[196:199], v214 offset:55296
	ds_read_b128 v[200:203], v214 offset:56320
	global_load_lds_dwordx4 v[204:205], off
	s_add_i32 m0, s26, 0x2000
	s_add_u32 s26, s30, 0x40080
	v_lshl_add_u64 v[204:205], v[216:217], 0, s[10:11]
	s_addc_u32 s27, s31, 0
	s_add_i32 s30, s56, s39
	global_load_lds_dwordx4 v[204:205], off
	v_lshl_add_u64 v[204:205], s[26:27], 0, v[176:177]
	s_mov_b32 m0, s30
	s_nop 0
	global_load_lds_dwordx4 v[204:205], off
	v_lshl_add_u64 v[204:205], s[26:27], 0, v[178:179]
	s_add_i32 m0, s30, 0x2000
	s_nop 0
	global_load_lds_dwordx4 v[204:205], off
	v_lshl_add_u64 v[204:205], v[218:219], 0, s[10:11]
	s_mov_b32 m0, s44
	s_nop 0
	global_load_lds_dwordx4 v[204:205], off
	v_lshl_add_u64 v[204:205], v[220:221], 0, s[10:11]
	s_mov_b32 m0, s45
	s_nop 0
	global_load_lds_dwordx4 v[204:205], off
	s_waitcnt vmcnt(8)
	s_waitcnt lgkmcnt(0)
	s_setprio 1
	s_barrier
	v_mfma_f32_16x16x32_bf16 v[60:63], v[128:131], v[160:163], v[60:63]
	v_mfma_f32_16x16x32_bf16 v[56:59], v[136:139], v[160:163], v[56:59]
	v_mfma_f32_16x16x32_bf16 v[44:47], v[128:131], v[168:171], v[44:47]
	v_mfma_f32_16x16x32_bf16 v[40:43], v[136:139], v[168:171], v[40:43]
	v_mfma_f32_16x16x32_bf16 v[28:31], v[128:131], v[188:191], v[28:31]
	v_mfma_f32_16x16x32_bf16 v[24:27], v[136:139], v[188:191], v[24:27]
	v_mfma_f32_16x16x32_bf16 v[12:15], v[128:131], v[196:199], v[12:15]
	v_mfma_f32_16x16x32_bf16 v[8:11], v[136:139], v[196:199], v[8:11]
	v_mfma_f32_16x16x32_bf16 v[60:63], v[132:135], v[164:167], v[60:63]
	v_mfma_f32_16x16x32_bf16 v[56:59], v[140:143], v[164:167], v[56:59]
	v_mfma_f32_16x16x32_bf16 v[44:47], v[132:135], v[172:175], v[44:47]
	v_mfma_f32_16x16x32_bf16 v[40:43], v[140:143], v[172:175], v[40:43]
	v_mfma_f32_16x16x32_bf16 v[28:31], v[132:135], v[192:195], v[28:31]
	v_mfma_f32_16x16x32_bf16 v[24:27], v[140:143], v[192:195], v[24:27]
	v_mfma_f32_16x16x32_bf16 v[12:15], v[132:135], v[200:203], v[12:15]
	v_mfma_f32_16x16x32_bf16 v[8:11], v[140:143], v[200:203], v[8:11]
	s_setprio 0
	s_setprio 1
	v_mfma_f32_16x16x32_bf16 v[52:55], v[144:147], v[160:163], v[52:55]
	v_mfma_f32_16x16x32_bf16 v[48:51], v[152:155], v[160:163], v[48:51]
	v_mfma_f32_16x16x32_bf16 v[36:39], v[144:147], v[168:171], v[36:39]
	v_mfma_f32_16x16x32_bf16 v[32:35], v[152:155], v[168:171], v[32:35]
	v_mfma_f32_16x16x32_bf16 v[20:23], v[144:147], v[188:191], v[20:23]
	v_mfma_f32_16x16x32_bf16 v[16:19], v[152:155], v[188:191], v[16:19]
	v_mfma_f32_16x16x32_bf16 v[4:7], v[144:147], v[196:199], v[4:7]
	v_mfma_f32_16x16x32_bf16 v[0:3], v[152:155], v[196:199], v[0:3]
	v_mfma_f32_16x16x32_bf16 v[52:55], v[148:151], v[164:167], v[52:55]
	v_mfma_f32_16x16x32_bf16 v[48:51], v[156:159], v[164:167], v[48:51]
	v_mfma_f32_16x16x32_bf16 v[36:39], v[148:151], v[172:175], v[36:39]
	v_mfma_f32_16x16x32_bf16 v[32:35], v[156:159], v[172:175], v[32:35]
	v_mfma_f32_16x16x32_bf16 v[20:23], v[148:151], v[192:195], v[20:23]
	v_mfma_f32_16x16x32_bf16 v[16:19], v[156:159], v[192:195], v[16:19]
	v_mfma_f32_16x16x32_bf16 v[4:7], v[148:151], v[200:203], v[4:7]
	v_mfma_f32_16x16x32_bf16 v[0:3], v[156:159], v[200:203], v[0:3]
	s_barrier
	s_setprio 0
	s_add_i32 s54, s54, 2
	s_add_u32 s52, s52, 0x100
	s_addc_u32 s53, s53, 0
	s_cmp_gt_u32 s54, 13
	s_mov_b64 s[26:27], s[28:29]

.LBB0_1309:
	s_ashr_i32 s23, s22, 31
	s_lshl_b64 s[24:25], s[22:23], 19
	s_add_u32 s24, s82, s24
	s_addc_u32 s25, s83, s25
	s_and_b64 s[26:27], s[0:1], exec
	s_cselect_b32 s23, s25, s31
	s_cselect_b32 s58, s24, s30
	s_ashr_i32 s21, s20, 31
	s_lshl_b64 s[26:27], s[20:21], 19
	s_add_u32 s26, s40, s26
	s_addc_u32 s27, s41, s27
	s_and_b64 s[36:37], s[0:1], exec
	s_cselect_b32 s21, s27, s35
	s_cselect_b32 s59, s26, s34
	s_add_u32 s30, s30, 0x40080
	s_addc_u32 s31, s31, 0
	s_add_u32 s60, s34, 0x100
	s_addc_u32 s61, s35, 0
	s_mov_b32 s62, -2
	s_nop 0
	s_nop 0
	s_nop 0
	s_nop 0
	s_nop 0
	s_nop 0
	s_nop 0
	s_nop 0
	s_nop 0
	s_nop 0
	s_nop 0
	s_nop 0
	s_nop 0
	s_nop 0
	ds_read_b128 v[144:147], v155
	ds_read_b128 v[148:151], v155 offset:1024
	ds_read_b128 v[160:163], v155 offset:2048
	ds_read_b128 v[164:167], v155 offset:3072
	ds_read_b128 v[168:171], v156
	ds_read_b128 v[172:175], v156 offset:1024
	ds_read_b128 v[176:179], v156 offset:2048
	ds_read_b128 v[180:183], v156 offset:3072
	s_add_u32 s34, s30, 0xfffc0080
	s_addc_u32 s35, s31, -1
	s_cmp_eq_u32 s62, 12
	s_cselect_b32 s37, s23, s35
	s_cselect_b32 s36, s58, s34
	s_cselect_b32 s35, s21, s61
	s_cselect_b32 s34, s59, s60
	v_lshl_add_u64 v[204:205], s[30:31], 0, v[136:137]
	s_add_i32 m0, s29, 0xc000
	ds_read_b128 v[184:187], v157
	ds_read_b128 v[188:191], v157 offset:1024
	ds_read_b128 v[192:195], v157 offset:2048
	ds_read_b128 v[196:199], v157 offset:3072
	ds_read_b128 v[200:203], v157 offset:4096
	ds_read_b128 v[210:213], v157 offset:5120
	ds_read_b128 v[214:217], v157 offset:6144
	ds_read_b128 v[218:221], v157 offset:7168
	global_load_lds_dwordx4 v[204:205], off
	v_lshl_add_u64 v[204:205], s[30:31], 0, v[138:139]
	s_add_i32 m0, s29, 0xe000
	s_nop 0
	global_load_lds_dwordx4 v[204:205], off
	s_waitcnt vmcnt(8)
	s_waitcnt lgkmcnt(0)
	s_setprio 1
	s_barrier
	v_mfma_f32_16x16x32_bf16 v[124:127], v[144:147], v[184:187], 0
	v_mfma_f32_16x16x32_bf16 v[120:123], v[160:163], v[184:187], 0
	v_mfma_f32_16x16x32_bf16 v[116:119], v[144:147], v[192:195], 0
	v_mfma_f32_16x16x32_bf16 v[104:107], v[160:163], v[192:195], 0
	v_mfma_f32_16x16x32_bf16 v[92:95], v[144:147], v[200:203], 0
	v_mfma_f32_16x16x32_bf16 v[88:91], v[160:163], v[200:203], 0
	v_mfma_f32_16x16x32_bf16 v[76:79], v[144:147], v[214:217], 0
	v_mfma_f32_16x16x32_bf16 v[72:75], v[160:163], v[214:217], 0
	v_mfma_f32_16x16x32_bf16 v[124:127], v[148:151], v[188:191], v[124:127]
	v_mfma_f32_16x16x32_bf16 v[120:123], v[164:167], v[188:191], v[120:123]
	v_mfma_f32_16x16x32_bf16 v[116:119], v[148:151], v[196:199], v[116:119]
	v_mfma_f32_16x16x32_bf16 v[104:107], v[164:167], v[196:199], v[104:107]
	v_mfma_f32_16x16x32_bf16 v[92:95], v[148:151], v[210:213], v[92:95]
	v_mfma_f32_16x16x32_bf16 v[88:91], v[164:167], v[210:213], v[88:91]
	v_mfma_f32_16x16x32_bf16 v[76:79], v[148:151], v[218:221], v[76:79]
	v_mfma_f32_16x16x32_bf16 v[72:75], v[164:167], v[218:221], v[72:75]
	s_setprio 0
	s_setprio 1
	v_mfma_f32_16x16x32_bf16 v[112:115], v[168:171], v[184:187], 0
	v_mfma_f32_16x16x32_bf16 v[108:111], v[176:179], v[184:187], 0
	v_mfma_f32_16x16x32_bf16 v[100:103], v[168:171], v[192:195], 0
	v_mfma_f32_16x16x32_bf16 v[96:99], v[176:179], v[192:195], 0
	v_mfma_f32_16x16x32_bf16 v[84:87], v[168:171], v[200:203], 0
	v_mfma_f32_16x16x32_bf16 v[80:83], v[176:179], v[200:203], 0
	v_mfma_f32_16x16x32_bf16 v[68:71], v[168:171], v[214:217], 0
	v_mfma_f32_16x16x32_bf16 v[64:67], v[176:179], v[214:217], 0
	v_mfma_f32_16x16x32_bf16 v[112:115], v[172:175], v[188:191], v[112:115]
	v_mfma_f32_16x16x32_bf16 v[108:111], v[180:183], v[188:191], v[108:111]
	v_mfma_f32_16x16x32_bf16 v[100:103], v[172:175], v[196:199], v[100:103]
	v_mfma_f32_16x16x32_bf16 v[96:99], v[180:183], v[196:199], v[96:99]
	v_mfma_f32_16x16x32_bf16 v[84:87], v[172:175], v[210:213], v[84:87]
	v_mfma_f32_16x16x32_bf16 v[80:83], v[180:183], v[210:213], v[80:83]
	v_mfma_f32_16x16x32_bf16 v[68:71], v[172:175], v[218:221], v[68:71]
	v_mfma_f32_16x16x32_bf16 v[64:67], v[180:183], v[218:221], v[64:67]
	s_barrier
	s_setprio 0
	s_add_i32 s63, s52, s42
	v_lshl_add_u64 v[204:205], s[34:35], 0, v[130:131]
	s_mov_b32 m0, s63
	ds_read_b128 v[184:187], v157 offset:16384
	ds_read_b128 v[188:191], v157 offset:17408
	ds_read_b128 v[192:195], v157 offset:18432
	ds_read_b128 v[196:199], v157 offset:19456
	ds_read_b128 v[200:203], v157 offset:20480
	ds_read_b128 v[210:213], v157 offset:21504
	ds_read_b128 v[214:217], v157 offset:22528
	ds_read_b128 v[218:221], v157 offset:23552
	global_load_lds_dwordx4 v[204:205], off
	s_add_i32 m0, s63, 0x2000
	s_add_u32 s64, s34, 0x40000
	v_lshl_add_u64 v[222:223], s[34:35], 0, v[134:135]
	s_addc_u32 s65, s35, 0
	s_add_i32 s63, s53, s42
	global_load_lds_dwordx4 v[222:223], off
	v_lshl_add_u64 v[224:225], s[64:65], 0, v[130:131]
	s_mov_b32 m0, s63
	v_lshl_add_u64 v[226:227], s[36:37], 0, v[132:133]
	global_load_lds_dwordx4 v[224:225], off
	v_lshl_add_u64 v[224:225], s[64:65], 0, v[134:135]
	s_add_i32 m0, s63, 0x2000
	s_nop 0
	global_load_lds_dwordx4 v[224:225], off
	v_lshl_add_u64 v[224:225], s[36:37], 0, v[128:129]
	s_mov_b32 m0, s29
	s_nop 0
	global_load_lds_dwordx4 v[224:225], off
	s_mov_b32 m0, s43
	s_nop 0
	global_load_lds_dwordx4 v[226:227], off
	s_waitcnt vmcnt(8)
	s_waitcnt lgkmcnt(0)
	s_setprio 1
	s_barrier
	v_mfma_f32_16x16x32_bf16 v[60:63], v[144:147], v[184:187], 0
	v_mfma_f32_16x16x32_bf16 v[56:59], v[160:163], v[184:187], 0
	v_mfma_f32_16x16x32_bf16 v[44:47], v[144:147], v[192:195], 0
	v_mfma_f32_16x16x32_bf16 v[40:43], v[160:163], v[192:195], 0
	v_mfma_f32_16x16x32_bf16 v[28:31], v[144:147], v[200:203], 0
	v_mfma_f32_16x16x32_bf16 v[24:27], v[160:163], v[200:203], 0
	v_mfma_f32_16x16x32_bf16 v[12:15], v[144:147], v[214:217], 0
	v_mfma_f32_16x16x32_bf16 v[8:11], v[160:163], v[214:217], 0
	v_mfma_f32_16x16x32_bf16 v[60:63], v[148:151], v[188:191], v[60:63]
	v_mfma_f32_16x16x32_bf16 v[56:59], v[164:167], v[188:191], v[56:59]
	v_mfma_f32_16x16x32_bf16 v[44:47], v[148:151], v[196:199], v[44:47]
	v_mfma_f32_16x16x32_bf16 v[40:43], v[164:167], v[196:199], v[40:43]
	v_mfma_f32_16x16x32_bf16 v[28:31], v[148:151], v[210:213], v[28:31]
	v_mfma_f32_16x16x32_bf16 v[24:27], v[164:167], v[210:213], v[24:27]
	v_mfma_f32_16x16x32_bf16 v[12:15], v[148:151], v[218:221], v[12:15]
	v_mfma_f32_16x16x32_bf16 v[8:11], v[164:167], v[218:221], v[8:11]
	s_setprio 0
	s_setprio 1
	v_mfma_f32_16x16x32_bf16 v[52:55], v[168:171], v[184:187], 0
	v_mfma_f32_16x16x32_bf16 v[48:51], v[176:179], v[184:187], 0
	v_mfma_f32_16x16x32_bf16 v[36:39], v[168:171], v[192:195], 0
	v_mfma_f32_16x16x32_bf16 v[32:35], v[176:179], v[192:195], 0
	v_mfma_f32_16x16x32_bf16 v[20:23], v[168:171], v[200:203], 0
	v_mfma_f32_16x16x32_bf16 v[16:19], v[176:179], v[200:203], 0
	v_mfma_f32_16x16x32_bf16 v[4:7], v[168:171], v[214:217], 0
	v_mfma_f32_16x16x32_bf16 v[0:3], v[176:179], v[214:217], 0
	v_mfma_f32_16x16x32_bf16 v[52:55], v[172:175], v[188:191], v[52:55]
	v_mfma_f32_16x16x32_bf16 v[48:51], v[180:183], v[188:191], v[48:51]
	v_mfma_f32_16x16x32_bf16 v[36:39], v[172:175], v[196:199], v[36:39]
	v_mfma_f32_16x16x32_bf16 v[32:35], v[180:183], v[196:199], v[32:35]
	v_mfma_f32_16x16x32_bf16 v[20:23], v[172:175], v[210:213], v[20:23]
	v_mfma_f32_16x16x32_bf16 v[16:19], v[180:183], v[210:213], v[16:19]
	v_mfma_f32_16x16x32_bf16 v[4:7], v[172:175], v[218:221], v[4:7]
	v_mfma_f32_16x16x32_bf16 v[0:3], v[180:183], v[218:221], v[0:3]
	s_barrier
	s_setprio 0
	s_add_i32 s63, 0, 0x18000
	v_add_u32_e32 v159, s63, v153
	s_add_i32 s64, 0, 0x1c000
	ds_read_b128 v[144:147], v159
	ds_read_b128 v[148:151], v159 offset:1024
	ds_read_b128 v[160:163], v159 offset:2048
	ds_read_b128 v[164:167], v159 offset:3072
	v_add_u32_e32 v159, s64, v153
	ds_read_b128 v[168:171], v159
	ds_read_b128 v[172:175], v159 offset:1024
	ds_read_b128 v[176:179], v159 offset:2048
	ds_read_b128 v[180:183], v159 offset:3072
	s_add_u32 s36, s36, 0x40000
	s_addc_u32 s37, s37, 0
	s_mov_b32 m0, s44
	v_lshl_add_u64 v[228:229], s[36:37], 0, v[128:129]
	ds_read_b128 v[184:187], v157 offset:32768
	ds_read_b128 v[188:191], v157 offset:33792
	ds_read_b128 v[192:195], v157 offset:34816
	ds_read_b128 v[196:199], v157 offset:35840
	ds_read_b128 v[200:203], v157 offset:36864
	ds_read_b128 v[210:213], v157 offset:37888
	ds_read_b128 v[214:217], v157 offset:38912
	ds_read_b128 v[218:221], v157 offset:39936
	global_load_lds_dwordx4 v[228:229], off
	v_lshl_add_u64 v[228:229], s[36:37], 0, v[132:133]
	s_mov_b32 m0, s45
	s_nop 0
	global_load_lds_dwordx4 v[228:229], off
	s_waitcnt vmcnt(8)
	s_waitcnt lgkmcnt(0)
	s_setprio 1
	s_barrier
	v_mfma_f32_16x16x32_bf16 v[124:127], v[144:147], v[184:187], v[124:127]
	v_mfma_f32_16x16x32_bf16 v[120:123], v[160:163], v[184:187], v[120:123]
	v_mfma_f32_16x16x32_bf16 v[116:119], v[144:147], v[192:195], v[116:119]
	v_mfma_f32_16x16x32_bf16 v[104:107], v[160:163], v[192:195], v[104:107]
	v_mfma_f32_16x16x32_bf16 v[92:95], v[144:147], v[200:203], v[92:95]
	v_mfma_f32_16x16x32_bf16 v[88:91], v[160:163], v[200:203], v[88:91]
	v_mfma_f32_16x16x32_bf16 v[76:79], v[144:147], v[214:217], v[76:79]
	v_mfma_f32_16x16x32_bf16 v[72:75], v[160:163], v[214:217], v[72:75]
	v_mfma_f32_16x16x32_bf16 v[124:127], v[148:151], v[188:191], v[124:127]
	v_mfma_f32_16x16x32_bf16 v[120:123], v[164:167], v[188:191], v[120:123]
	v_mfma_f32_16x16x32_bf16 v[116:119], v[148:151], v[196:199], v[116:119]
	v_mfma_f32_16x16x32_bf16 v[104:107], v[164:167], v[196:199], v[104:107]
	v_mfma_f32_16x16x32_bf16 v[92:95], v[148:151], v[210:213], v[92:95]
	v_mfma_f32_16x16x32_bf16 v[88:91], v[164:167], v[210:213], v[88:91]
	v_mfma_f32_16x16x32_bf16 v[76:79], v[148:151], v[218:221], v[76:79]
	v_mfma_f32_16x16x32_bf16 v[72:75], v[164:167], v[218:221], v[72:75]
	s_setprio 0
	s_setprio 1
	v_mfma_f32_16x16x32_bf16 v[112:115], v[168:171], v[184:187], v[112:115]
	v_mfma_f32_16x16x32_bf16 v[108:111], v[176:179], v[184:187], v[108:111]
	v_mfma_f32_16x16x32_bf16 v[100:103], v[168:171], v[192:195], v[100:103]
	v_mfma_f32_16x16x32_bf16 v[96:99], v[176:179], v[192:195], v[96:99]
	v_mfma_f32_16x16x32_bf16 v[84:87], v[168:171], v[200:203], v[84:87]
	v_mfma_f32_16x16x32_bf16 v[80:83], v[176:179], v[200:203], v[80:83]
	v_mfma_f32_16x16x32_bf16 v[68:71], v[168:171], v[214:217], v[68:71]
	v_mfma_f32_16x16x32_bf16 v[64:67], v[176:179], v[214:217], v[64:67]
	v_mfma_f32_16x16x32_bf16 v[112:115], v[172:175], v[188:191], v[112:115]
	v_mfma_f32_16x16x32_bf16 v[108:111], v[180:183], v[188:191], v[108:111]
	v_mfma_f32_16x16x32_bf16 v[100:103], v[172:175], v[196:199], v[100:103]
	v_mfma_f32_16x16x32_bf16 v[96:99], v[180:183], v[196:199], v[96:99]
	v_mfma_f32_16x16x32_bf16 v[84:87], v[172:175], v[210:213], v[84:87]
	v_mfma_f32_16x16x32_bf16 v[80:83], v[180:183], v[210:213], v[80:83]
	v_mfma_f32_16x16x32_bf16 v[68:71], v[172:175], v[218:221], v[68:71]
	v_mfma_f32_16x16x32_bf16 v[64:67], v[180:183], v[218:221], v[64:67]
	s_barrier
	s_setprio 0
	s_add_i32 s36, s63, s42
	v_lshl_add_u64 v[204:205], v[204:205], 0, s[8:9]
	s_mov_b32 m0, s36
	ds_read_b128 v[184:187], v157 offset:49152
	ds_read_b128 v[188:191], v157 offset:50176
	ds_read_b128 v[192:195], v157 offset:51200
	ds_read_b128 v[196:199], v157 offset:52224
	ds_read_b128 v[200:203], v157 offset:53248
	ds_read_b128 v[210:213], v157 offset:54272
	ds_read_b128 v[214:217], v157 offset:55296
	ds_read_b128 v[218:221], v157 offset:56320
	global_load_lds_dwordx4 v[204:205], off
	s_add_i32 m0, s36, 0x2000
	s_add_u32 s34, s34, 0x40080
	v_lshl_add_u64 v[204:205], v[222:223], 0, s[8:9]
	s_addc_u32 s35, s35, 0
	s_add_i32 s36, s64, s42
	global_load_lds_dwordx4 v[204:205], off
	v_lshl_add_u64 v[204:205], s[34:35], 0, v[130:131]
	s_mov_b32 m0, s36
	s_nop 0
	global_load_lds_dwordx4 v[204:205], off
	v_lshl_add_u64 v[204:205], s[34:35], 0, v[134:135]
	s_add_i32 m0, s36, 0x2000
	s_nop 0
	global_load_lds_dwordx4 v[204:205], off
	v_lshl_add_u64 v[204:205], v[224:225], 0, s[8:9]
	s_mov_b32 m0, s49
	s_nop 0
	global_load_lds_dwordx4 v[204:205], off
	v_lshl_add_u64 v[204:205], v[226:227], 0, s[8:9]
	s_mov_b32 m0, s50
	s_nop 0
	global_load_lds_dwordx4 v[204:205], off
	s_waitcnt vmcnt(8)
	s_waitcnt lgkmcnt(0)
	s_setprio 1
	s_barrier
	v_mfma_f32_16x16x32_bf16 v[60:63], v[144:147], v[184:187], v[60:63]
	v_mfma_f32_16x16x32_bf16 v[56:59], v[160:163], v[184:187], v[56:59]
	v_mfma_f32_16x16x32_bf16 v[44:47], v[144:147], v[192:195], v[44:47]
	v_mfma_f32_16x16x32_bf16 v[40:43], v[160:163], v[192:195], v[40:43]
	v_mfma_f32_16x16x32_bf16 v[28:31], v[144:147], v[200:203], v[28:31]
	v_mfma_f32_16x16x32_bf16 v[24:27], v[160:163], v[200:203], v[24:27]
	v_mfma_f32_16x16x32_bf16 v[12:15], v[144:147], v[214:217], v[12:15]
	v_mfma_f32_16x16x32_bf16 v[8:11], v[160:163], v[214:217], v[8:11]
	v_mfma_f32_16x16x32_bf16 v[60:63], v[148:151], v[188:191], v[60:63]
	v_mfma_f32_16x16x32_bf16 v[56:59], v[164:167], v[188:191], v[56:59]
	v_mfma_f32_16x16x32_bf16 v[44:47], v[148:151], v[196:199], v[44:47]
	v_mfma_f32_16x16x32_bf16 v[40:43], v[164:167], v[196:199], v[40:43]
	v_mfma_f32_16x16x32_bf16 v[28:31], v[148:151], v[210:213], v[28:31]
	v_mfma_f32_16x16x32_bf16 v[24:27], v[164:167], v[210:213], v[24:27]
	v_mfma_f32_16x16x32_bf16 v[12:15], v[148:151], v[218:221], v[12:15]
	v_mfma_f32_16x16x32_bf16 v[8:11], v[164:167], v[218:221], v[8:11]
	s_setprio 0
	s_setprio 1
	v_mfma_f32_16x16x32_bf16 v[52:55], v[168:171], v[184:187], v[52:55]
	v_mfma_f32_16x16x32_bf16 v[48:51], v[176:179], v[184:187], v[48:51]
	v_mfma_f32_16x16x32_bf16 v[36:39], v[168:171], v[192:195], v[36:39]
	v_mfma_f32_16x16x32_bf16 v[32:35], v[176:179], v[192:195], v[32:35]
	v_mfma_f32_16x16x32_bf16 v[20:23], v[168:171], v[200:203], v[20:23]
	v_mfma_f32_16x16x32_bf16 v[16:19], v[176:179], v[200:203], v[16:19]
	v_mfma_f32_16x16x32_bf16 v[4:7], v[168:171], v[214:217], v[4:7]
	v_mfma_f32_16x16x32_bf16 v[0:3], v[176:179], v[214:217], v[0:3]
	v_mfma_f32_16x16x32_bf16 v[52:55], v[172:175], v[188:191], v[52:55]
	v_mfma_f32_16x16x32_bf16 v[48:51], v[180:183], v[188:191], v[48:51]
	v_mfma_f32_16x16x32_bf16 v[36:39], v[172:175], v[196:199], v[36:39]
	v_mfma_f32_16x16x32_bf16 v[32:35], v[180:183], v[196:199], v[32:35]
	v_mfma_f32_16x16x32_bf16 v[20:23], v[172:175], v[210:213], v[20:23]
	v_mfma_f32_16x16x32_bf16 v[16:19], v[180:183], v[210:213], v[16:19]
	v_mfma_f32_16x16x32_bf16 v[4:7], v[172:175], v[218:221], v[4:7]
	v_mfma_f32_16x16x32_bf16 v[0:3], v[180:183], v[218:221], v[0:3]
	s_barrier
	s_setprio 0
	s_add_i32 s62, s62, 2
	s_add_u32 s30, s30, 0x100
	s_addc_u32 s31, s31, 0
	s_add_u32 s60, s60, 0x100
	s_addc_u32 s61, s61, 0
	s_cmp_gt_u32 s62, 13

.LBB0_1388:
	s_ashr_i32 s19, s18, 31
	s_lshl_b64 s[20:21], s[18:19], 21
	s_add_u32 s20, s80, s20
	s_addc_u32 s21, s81, s21
	s_and_b64 s[22:23], s[4:5], exec
	s_cselect_b32 s3, s21, s29
	s_cselect_b32 s19, s20, s28
	s_ashr_i32 s17, s16, 31
	s_lshl_b64 s[22:23], s[16:17], 21
	s_add_u32 s22, s33, s22
	s_addc_u32 s23, s52, s23
	s_and_b64 s[34:35], s[4:5], exec
	s_cselect_b32 s17, s23, s31
	s_cselect_b32 s25, s22, s30
	s_add_u32 s54, s30, 0x100
	s_addc_u32 s55, s31, 0
	s_mov_b32 s56, -2
	s_waitcnt lgkmcnt(0)
	ds_read_b128 v[128:131], v212
	ds_read_b128 v[132:135], v212 offset:1024
	ds_read_b128 v[136:139], v212 offset:2048
	ds_read_b128 v[140:143], v212 offset:3072
	ds_read_b128 v[144:147], v213
	ds_read_b128 v[148:151], v213 offset:1024
	ds_read_b128 v[152:155], v213 offset:2048
	ds_read_b128 v[156:159], v213 offset:3072
	s_add_u32 s30, s28, 0x100
	s_addc_u32 s31, s29, 0
	s_cmp_eq_u32 s56, 60
	s_cselect_b32 s37, s3, s31
	s_cselect_b32 s36, s19, s30
	s_cselect_b32 s35, s17, s55
	s_cselect_b32 s34, s25, s54
	v_lshl_add_u64 v[204:205], s[28:29], 0, v[180:181]
	s_add_i32 m0, s27, 0xc000
	ds_read_b128 v[160:163], v214
	ds_read_b128 v[164:167], v214 offset:1024
	ds_read_b128 v[168:171], v214 offset:2048
	ds_read_b128 v[172:175], v214 offset:3072
	ds_read_b128 v[188:191], v214 offset:4096
	ds_read_b128 v[192:195], v214 offset:5120
	ds_read_b128 v[196:199], v214 offset:6144
	ds_read_b128 v[200:203], v214 offset:7168
	global_load_lds_dwordx4 v[204:205], off
	v_lshl_add_u64 v[204:205], s[28:29], 0, v[182:183]
	s_add_i32 m0, s27, 0xe000
	s_nop 0
	global_load_lds_dwordx4 v[204:205], off
	s_waitcnt vmcnt(8)
	s_waitcnt lgkmcnt(0)
	s_setprio 1
	s_barrier
	v_mfma_f32_16x16x32_bf16 v[124:127], v[128:131], v[160:163], 0
	v_mfma_f32_16x16x32_bf16 v[120:123], v[136:139], v[160:163], 0
	v_mfma_f32_16x16x32_bf16 v[108:111], v[128:131], v[168:171], 0
	v_mfma_f32_16x16x32_bf16 v[104:107], v[136:139], v[168:171], 0
	v_mfma_f32_16x16x32_bf16 v[92:95], v[128:131], v[188:191], 0
	v_mfma_f32_16x16x32_bf16 v[88:91], v[136:139], v[188:191], 0
	v_mfma_f32_16x16x32_bf16 v[76:79], v[128:131], v[196:199], 0
	v_mfma_f32_16x16x32_bf16 v[72:75], v[136:139], v[196:199], 0
	v_mfma_f32_16x16x32_bf16 v[124:127], v[132:135], v[164:167], v[124:127]
	v_mfma_f32_16x16x32_bf16 v[120:123], v[140:143], v[164:167], v[120:123]
	v_mfma_f32_16x16x32_bf16 v[108:111], v[132:135], v[172:175], v[108:111]
	v_mfma_f32_16x16x32_bf16 v[104:107], v[140:143], v[172:175], v[104:107]
	v_mfma_f32_16x16x32_bf16 v[92:95], v[132:135], v[192:195], v[92:95]
	v_mfma_f32_16x16x32_bf16 v[88:91], v[140:143], v[192:195], v[88:91]
	v_mfma_f32_16x16x32_bf16 v[76:79], v[132:135], v[200:203], v[76:79]
	v_mfma_f32_16x16x32_bf16 v[72:75], v[140:143], v[200:203], v[72:75]
	s_setprio 0
	s_setprio 1
	v_mfma_f32_16x16x32_bf16 v[116:119], v[144:147], v[160:163], 0
	v_mfma_f32_16x16x32_bf16 v[112:115], v[152:155], v[160:163], 0
	v_mfma_f32_16x16x32_bf16 v[100:103], v[144:147], v[168:171], 0
	v_mfma_f32_16x16x32_bf16 v[96:99], v[152:155], v[168:171], 0
	v_mfma_f32_16x16x32_bf16 v[84:87], v[144:147], v[188:191], 0
	v_mfma_f32_16x16x32_bf16 v[80:83], v[152:155], v[188:191], 0
	v_mfma_f32_16x16x32_bf16 v[68:71], v[144:147], v[196:199], 0
	v_mfma_f32_16x16x32_bf16 v[64:67], v[152:155], v[196:199], 0
	v_mfma_f32_16x16x32_bf16 v[116:119], v[148:151], v[164:167], v[116:119]
	v_mfma_f32_16x16x32_bf16 v[112:115], v[156:159], v[164:167], v[112:115]
	v_mfma_f32_16x16x32_bf16 v[100:103], v[148:151], v[172:175], v[100:103]
	v_mfma_f32_16x16x32_bf16 v[96:99], v[156:159], v[172:175], v[96:99]
	v_mfma_f32_16x16x32_bf16 v[84:87], v[148:151], v[192:195], v[84:87]
	v_mfma_f32_16x16x32_bf16 v[80:83], v[156:159], v[192:195], v[80:83]
	v_mfma_f32_16x16x32_bf16 v[68:71], v[148:151], v[200:203], v[68:71]
	v_mfma_f32_16x16x32_bf16 v[64:67], v[156:159], v[200:203], v[64:67]
	s_barrier
	s_setprio 0
	s_add_i32 s28, s51, s40
	v_lshl_add_u64 v[204:205], s[34:35], 0, v[176:177]
	s_mov_b32 m0, s28
	ds_read_b128 v[160:163], v214 offset:16384
	ds_read_b128 v[164:167], v214 offset:17408
	ds_read_b128 v[168:171], v214 offset:18432
	ds_read_b128 v[172:175], v214 offset:19456
	ds_read_b128 v[188:191], v214 offset:20480
	ds_read_b128 v[192:195], v214 offset:21504
	ds_read_b128 v[196:199], v214 offset:22528
	ds_read_b128 v[200:203], v214 offset:23552
	global_load_lds_dwordx4 v[204:205], off
	s_add_i32 m0, s28, 0x2000
	s_add_u32 s28, s34, 0x100000
	v_lshl_add_u64 v[216:217], s[34:35], 0, v[178:179]
	s_addc_u32 s29, s35, 0
	s_add_i32 s57, s53, s40
	global_load_lds_dwordx4 v[216:217], off
	v_lshl_add_u64 v[218:219], s[28:29], 0, v[176:177]
	s_mov_b32 m0, s57
	v_lshl_add_u64 v[220:221], s[36:37], 0, v[178:179]
	global_load_lds_dwordx4 v[218:219], off
	v_lshl_add_u64 v[218:219], s[28:29], 0, v[178:179]
	s_add_i32 m0, s57, 0x2000
	s_nop 0
	global_load_lds_dwordx4 v[218:219], off
	v_lshl_add_u64 v[218:219], s[36:37], 0, v[176:177]
	s_mov_b32 m0, s27
	s_nop 0
	global_load_lds_dwordx4 v[218:219], off
	s_mov_b32 m0, s41
	s_nop 0
	global_load_lds_dwordx4 v[220:221], off
	s_waitcnt vmcnt(8)
	s_waitcnt lgkmcnt(0)
	s_setprio 1
	s_barrier
	v_mfma_f32_16x16x32_bf16 v[60:63], v[128:131], v[160:163], 0
	v_mfma_f32_16x16x32_bf16 v[56:59], v[136:139], v[160:163], 0
	v_mfma_f32_16x16x32_bf16 v[44:47], v[128:131], v[168:171], 0
	v_mfma_f32_16x16x32_bf16 v[40:43], v[136:139], v[168:171], 0
	v_mfma_f32_16x16x32_bf16 v[28:31], v[128:131], v[188:191], 0
	v_mfma_f32_16x16x32_bf16 v[24:27], v[136:139], v[188:191], 0
	v_mfma_f32_16x16x32_bf16 v[12:15], v[128:131], v[196:199], 0
	v_mfma_f32_16x16x32_bf16 v[8:11], v[136:139], v[196:199], 0
	v_mfma_f32_16x16x32_bf16 v[60:63], v[132:135], v[164:167], v[60:63]
	v_mfma_f32_16x16x32_bf16 v[56:59], v[140:143], v[164:167], v[56:59]
	v_mfma_f32_16x16x32_bf16 v[44:47], v[132:135], v[172:175], v[44:47]
	v_mfma_f32_16x16x32_bf16 v[40:43], v[140:143], v[172:175], v[40:43]
	v_mfma_f32_16x16x32_bf16 v[28:31], v[132:135], v[192:195], v[28:31]
	v_mfma_f32_16x16x32_bf16 v[24:27], v[140:143], v[192:195], v[24:27]
	v_mfma_f32_16x16x32_bf16 v[12:15], v[132:135], v[200:203], v[12:15]
	v_mfma_f32_16x16x32_bf16 v[8:11], v[140:143], v[200:203], v[8:11]
	s_setprio 0
	s_setprio 1
	v_mfma_f32_16x16x32_bf16 v[52:55], v[144:147], v[160:163], 0
	v_mfma_f32_16x16x32_bf16 v[48:51], v[152:155], v[160:163], 0
	v_mfma_f32_16x16x32_bf16 v[36:39], v[144:147], v[168:171], 0
	v_mfma_f32_16x16x32_bf16 v[32:35], v[152:155], v[168:171], 0
	v_mfma_f32_16x16x32_bf16 v[20:23], v[144:147], v[188:191], 0
	v_mfma_f32_16x16x32_bf16 v[16:19], v[152:155], v[188:191], 0
	v_mfma_f32_16x16x32_bf16 v[4:7], v[144:147], v[196:199], 0
	v_mfma_f32_16x16x32_bf16 v[0:3], v[152:155], v[196:199], 0
	v_mfma_f32_16x16x32_bf16 v[52:55], v[148:151], v[164:167], v[52:55]
	v_mfma_f32_16x16x32_bf16 v[48:51], v[156:159], v[164:167], v[48:51]
	v_mfma_f32_16x16x32_bf16 v[36:39], v[148:151], v[172:175], v[36:39]
	v_mfma_f32_16x16x32_bf16 v[32:35], v[156:159], v[172:175], v[32:35]
	v_mfma_f32_16x16x32_bf16 v[20:23], v[148:151], v[192:195], v[20:23]
	v_mfma_f32_16x16x32_bf16 v[16:19], v[156:159], v[192:195], v[16:19]
	v_mfma_f32_16x16x32_bf16 v[4:7], v[148:151], v[200:203], v[4:7]
	v_mfma_f32_16x16x32_bf16 v[0:3], v[156:159], v[200:203], v[0:3]
	s_barrier
	s_setprio 0
	s_add_i32 s57, 0, 0x18000
	s_add_i32 s58, 0, 0x1c000
	v_add_u32_e32 v140, s57, v210
	v_add_u32_e32 v156, s58, v210
	ds_read_b128 v[128:131], v140
	ds_read_b128 v[132:135], v140 offset:1024
	ds_read_b128 v[136:139], v140 offset:2048
	ds_read_b128 v[140:143], v140 offset:3072
	ds_read_b128 v[144:147], v156
	ds_read_b128 v[148:151], v156 offset:1024
	ds_read_b128 v[152:155], v156 offset:2048
	ds_read_b128 v[156:159], v156 offset:3072
	s_add_u32 s28, s36, 0x100000
	s_addc_u32 s29, s37, 0
	s_mov_b32 m0, s42
	v_lshl_add_u64 v[222:223], s[28:29], 0, v[176:177]
	ds_read_b128 v[160:163], v214 offset:32768
	ds_read_b128 v[164:167], v214 offset:33792
	ds_read_b128 v[168:171], v214 offset:34816
	ds_read_b128 v[172:175], v214 offset:35840
	ds_read_b128 v[188:191], v214 offset:36864
	ds_read_b128 v[192:195], v214 offset:37888
	ds_read_b128 v[196:199], v214 offset:38912
	ds_read_b128 v[200:203], v214 offset:39936
	global_load_lds_dwordx4 v[222:223], off
	v_lshl_add_u64 v[222:223], s[28:29], 0, v[178:179]
	s_mov_b32 m0, s43
	s_nop 0
	global_load_lds_dwordx4 v[222:223], off
	s_waitcnt vmcnt(8)
	s_waitcnt lgkmcnt(0)
	s_setprio 1
	s_barrier
	v_mfma_f32_16x16x32_bf16 v[124:127], v[128:131], v[160:163], v[124:127]
	v_mfma_f32_16x16x32_bf16 v[120:123], v[136:139], v[160:163], v[120:123]
	v_mfma_f32_16x16x32_bf16 v[108:111], v[128:131], v[168:171], v[108:111]
	v_mfma_f32_16x16x32_bf16 v[104:107], v[136:139], v[168:171], v[104:107]
	v_mfma_f32_16x16x32_bf16 v[92:95], v[128:131], v[188:191], v[92:95]
	v_mfma_f32_16x16x32_bf16 v[88:91], v[136:139], v[188:191], v[88:91]
	v_mfma_f32_16x16x32_bf16 v[76:79], v[128:131], v[196:199], v[76:79]
	v_mfma_f32_16x16x32_bf16 v[72:75], v[136:139], v[196:199], v[72:75]
	v_mfma_f32_16x16x32_bf16 v[124:127], v[132:135], v[164:167], v[124:127]
	v_mfma_f32_16x16x32_bf16 v[120:123], v[140:143], v[164:167], v[120:123]
	v_mfma_f32_16x16x32_bf16 v[108:111], v[132:135], v[172:175], v[108:111]
	v_mfma_f32_16x16x32_bf16 v[104:107], v[140:143], v[172:175], v[104:107]
	v_mfma_f32_16x16x32_bf16 v[92:95], v[132:135], v[192:195], v[92:95]
	v_mfma_f32_16x16x32_bf16 v[88:91], v[140:143], v[192:195], v[88:91]
	v_mfma_f32_16x16x32_bf16 v[76:79], v[132:135], v[200:203], v[76:79]
	v_mfma_f32_16x16x32_bf16 v[72:75], v[140:143], v[200:203], v[72:75]
	s_setprio 0
	s_setprio 1
	v_mfma_f32_16x16x32_bf16 v[116:119], v[144:147], v[160:163], v[116:119]
	v_mfma_f32_16x16x32_bf16 v[112:115], v[152:155], v[160:163], v[112:115]
	v_mfma_f32_16x16x32_bf16 v[100:103], v[144:147], v[168:171], v[100:103]
	v_mfma_f32_16x16x32_bf16 v[96:99], v[152:155], v[168:171], v[96:99]
	v_mfma_f32_16x16x32_bf16 v[84:87], v[144:147], v[188:191], v[84:87]
	v_mfma_f32_16x16x32_bf16 v[80:83], v[152:155], v[188:191], v[80:83]
	v_mfma_f32_16x16x32_bf16 v[68:71], v[144:147], v[196:199], v[68:71]
	v_mfma_f32_16x16x32_bf16 v[64:67], v[152:155], v[196:199], v[64:67]
	v_mfma_f32_16x16x32_bf16 v[116:119], v[148:151], v[164:167], v[116:119]
	v_mfma_f32_16x16x32_bf16 v[112:115], v[156:159], v[164:167], v[112:115]
	v_mfma_f32_16x16x32_bf16 v[100:103], v[148:151], v[172:175], v[100:103]
	v_mfma_f32_16x16x32_bf16 v[96:99], v[156:159], v[172:175], v[96:99]
	v_mfma_f32_16x16x32_bf16 v[84:87], v[148:151], v[192:195], v[84:87]
	v_mfma_f32_16x16x32_bf16 v[80:83], v[156:159], v[192:195], v[80:83]
	v_mfma_f32_16x16x32_bf16 v[68:71], v[148:151], v[200:203], v[68:71]
	v_mfma_f32_16x16x32_bf16 v[64:67], v[156:159], v[200:203], v[64:67]
	s_barrier
	s_setprio 0
	s_add_i32 s28, s57, s40
	v_lshl_add_u64 v[204:205], v[204:205], 0, s[12:13]
	s_mov_b32 m0, s28
	ds_read_b128 v[160:163], v214 offset:49152
	ds_read_b128 v[164:167], v214 offset:50176
	ds_read_b128 v[168:171], v214 offset:51200
	ds_read_b128 v[172:175], v214 offset:52224
	ds_read_b128 v[188:191], v214 offset:53248
	ds_read_b128 v[192:195], v214 offset:54272
	ds_read_b128 v[196:199], v214 offset:55296
	ds_read_b128 v[200:203], v214 offset:56320
	global_load_lds_dwordx4 v[204:205], off
	s_add_i32 m0, s28, 0x2000
	s_add_u32 s28, s34, 0x100080
	v_lshl_add_u64 v[204:205], v[216:217], 0, s[12:13]
	s_addc_u32 s29, s35, 0
	s_add_i32 s34, s58, s40
	global_load_lds_dwordx4 v[204:205], off
	v_lshl_add_u64 v[204:205], s[28:29], 0, v[176:177]
	s_mov_b32 m0, s34
	s_nop 0
	global_load_lds_dwordx4 v[204:205], off
	v_lshl_add_u64 v[204:205], s[28:29], 0, v[178:179]
	s_add_i32 m0, s34, 0x2000
	s_nop 0
	global_load_lds_dwordx4 v[204:205], off
	v_lshl_add_u64 v[204:205], v[218:219], 0, s[12:13]
	s_mov_b32 m0, s45
	s_nop 0
	global_load_lds_dwordx4 v[204:205], off
	v_lshl_add_u64 v[204:205], v[220:221], 0, s[12:13]
	s_mov_b32 m0, s48
	s_nop 0
	global_load_lds_dwordx4 v[204:205], off
	s_waitcnt vmcnt(8)
	s_waitcnt lgkmcnt(0)
	s_setprio 1
	s_barrier
	v_mfma_f32_16x16x32_bf16 v[60:63], v[128:131], v[160:163], v[60:63]
	v_mfma_f32_16x16x32_bf16 v[56:59], v[136:139], v[160:163], v[56:59]
	v_mfma_f32_16x16x32_bf16 v[44:47], v[128:131], v[168:171], v[44:47]
	v_mfma_f32_16x16x32_bf16 v[40:43], v[136:139], v[168:171], v[40:43]
	v_mfma_f32_16x16x32_bf16 v[28:31], v[128:131], v[188:191], v[28:31]
	v_mfma_f32_16x16x32_bf16 v[24:27], v[136:139], v[188:191], v[24:27]
	v_mfma_f32_16x16x32_bf16 v[12:15], v[128:131], v[196:199], v[12:15]
	v_mfma_f32_16x16x32_bf16 v[8:11], v[136:139], v[196:199], v[8:11]
	v_mfma_f32_16x16x32_bf16 v[60:63], v[132:135], v[164:167], v[60:63]
	v_mfma_f32_16x16x32_bf16 v[56:59], v[140:143], v[164:167], v[56:59]
	v_mfma_f32_16x16x32_bf16 v[44:47], v[132:135], v[172:175], v[44:47]
	v_mfma_f32_16x16x32_bf16 v[40:43], v[140:143], v[172:175], v[40:43]
	v_mfma_f32_16x16x32_bf16 v[28:31], v[132:135], v[192:195], v[28:31]
	v_mfma_f32_16x16x32_bf16 v[24:27], v[140:143], v[192:195], v[24:27]
	v_mfma_f32_16x16x32_bf16 v[12:15], v[132:135], v[200:203], v[12:15]
	v_mfma_f32_16x16x32_bf16 v[8:11], v[140:143], v[200:203], v[8:11]
	s_setprio 0
	s_setprio 1
	v_mfma_f32_16x16x32_bf16 v[52:55], v[144:147], v[160:163], v[52:55]
	v_mfma_f32_16x16x32_bf16 v[48:51], v[152:155], v[160:163], v[48:51]
	v_mfma_f32_16x16x32_bf16 v[36:39], v[144:147], v[168:171], v[36:39]
	v_mfma_f32_16x16x32_bf16 v[32:35], v[152:155], v[168:171], v[32:35]
	v_mfma_f32_16x16x32_bf16 v[20:23], v[144:147], v[188:191], v[20:23]
	v_mfma_f32_16x16x32_bf16 v[16:19], v[152:155], v[188:191], v[16:19]
	v_mfma_f32_16x16x32_bf16 v[4:7], v[144:147], v[196:199], v[4:7]
	v_mfma_f32_16x16x32_bf16 v[0:3], v[152:155], v[196:199], v[0:3]
	v_mfma_f32_16x16x32_bf16 v[52:55], v[148:151], v[164:167], v[52:55]
	v_mfma_f32_16x16x32_bf16 v[48:51], v[156:159], v[164:167], v[48:51]
	v_mfma_f32_16x16x32_bf16 v[36:39], v[148:151], v[172:175], v[36:39]
	v_mfma_f32_16x16x32_bf16 v[32:35], v[156:159], v[172:175], v[32:35]
	v_mfma_f32_16x16x32_bf16 v[20:23], v[148:151], v[192:195], v[20:23]
	v_mfma_f32_16x16x32_bf16 v[16:19], v[156:159], v[192:195], v[16:19]
	v_mfma_f32_16x16x32_bf16 v[4:7], v[148:151], v[200:203], v[4:7]
	v_mfma_f32_16x16x32_bf16 v[0:3], v[156:159], v[200:203], v[0:3]
	s_barrier
	s_setprio 0
	s_add_i32 s56, s56, 2
	s_add_u32 s54, s54, 0x100
	s_addc_u32 s55, s55, 0
	s_cmp_gt_u32 s56, 61
	s_mov_b64 s[28:29], s[30:31]
